# GEMM K-loops: LDS-DMA loads use saddr form (no VALU 64-bit address adds)
# speedup vs baseline: 1.0019x; 1.0019x over previous
; #define PG8_STAGE(bufoff, gbase, voff) do { _Pragma("unroll") for (int _i = 0; _i < 2; ++_i) \
;         __builtin_amdgcn_global_load_lds((const unsigned*)((const char*)(gbase) + (voff)[_i]), (PG8_LAS unsigned*)(lds + (bufoff) + ldsw + _i * 8192), 16, 0, 0); } while (0)
; #define PG8_LDA(dst, b, h) do { _Pragma("unroll") for (int m = 0; m < 4; ++m) _Pragma("unroll") for (int k = 0; k < 2; ++k) dst[m][k] = *(const PG8_LAS bf16x8*)(lds + PG8_SA(b, h) + aoff + m * 2048 + k * 1024); } while (0)
; #define PG8_LDB(dst, b, h) do { _Pragma("unroll") for (int n = 0; n < 2; ++n) _Pragma("unroll") for (int k = 0; k < 2; ++k) dst[n][k] = *(const PG8_LAS bf16x8*)(lds + PG8_SB(b, h) + boff + n * 2048 + k * 1024); } while (0)
; #define PG8_MMA(ai, bj, At, Bt) do { __builtin_amdgcn_s_setprio(1); _Pragma("unroll") for (int m = 0; m < 4; ++m) _Pragma("unroll") for (int n = 0; n < 2; ++n) _Pragma("unroll") for (int k = 0; k < 2; ++k) \
;         acc[ai][bj][m][n] = __builtin_amdgcn_mfma_f32_16x16x32_bf16(Bt[n][k], At[m][k], acc[ai][bj][m][n], 0, 0, 0); __builtin_amdgcn_s_setprio(0); } while (0)
; #define PG8_WAIT_V(n) asm volatile("s_waitcnt vmcnt(" #n ")" ::: "memory")
; template <class Epi, class Sched, bool ALIGN_EPI = false, bool SP2 = false, bool ABLK = false, bool BBLK = false>
; __device__ __forceinline__ void gemm_phase(PG8_LAS unsigned char* lds, const Gemm g, const Sched& S, const Epi& E) {
;     ...
;         for (int t = 0; t < nt; t += 2) {
;             const bool last = (t == nt - 2);
;             const char* a1 = cA + (size_t)(t + 1) * kstepA;
;             const char* a2 = last ? nA : cA + (size_t)(t + 2) * kstepA; const char* b2 = last ? nB : cB + (size_t)(t + 2) * kstepB;
;             const char* a3 = a2 + kstepA; const char* b3 = b2 + kstepB;
;             if (last && has_next) S.a_ready(nxt);
;             if constexpr (SP2) {
;             PG8_LDB(B0, 0, 0); PG8_LDB(B1, 0, 1); PG8_SCHED; PG8_LDA(At, 0, 0); PG8_STAGE(PG8_SA(1, 1), a1 + hstepA, voffA);
;             PG8_WAIT_V(8); PG8_WAIT_L(0); PG8_BAR; PG8_MMA(0, 0, At, B0); PG8_MMA(0, 1, At, B1); PG8_BAR; PG8_SCHED;
;             PG8_LDA(At, 0, 1); PG8_STAGE(PG8_SB(0, 0), b2, voffB); PG8_STAGE(PG8_SB(0, 1), b2 + hstepB, voffB); PG8_STAGE(PG8_SA(0, 0), a2, voffA);
;             PG8_WAIT_V(8); PG8_WAIT_L(0); PG8_BAR; PG8_MMA(1, 0, At, B0); PG8_MMA(1, 1, At, B1); PG8_BAR; PG8_SCHED;
.LBB0_185:
	s_add_u32 s13, s20, 0x4000
	s_addc_u32 s22, s21, 0
	s_cmp_eq_u32 vcc_hi, 28
	s_cselect_b32 s26, s70, s13
	s_cselect_b32 s27, s9, s22
	s_cselect_b32 s24, s71, s77
	s_cselect_b32 s25, s7, vcc_lo
	s_add_u32 s22, s26, 0x8000
	s_addc_u32 s23, s27, 0
	s_add_i32 s13, 0, 0x10000
	v_add_u32_e32 v36, s13, v160
	s_add_i32 s88, 0, 0x14000
	ds_read_b128 v[152:155], v36
	ds_read_b128 v[156:159], v36 offset:1024
	ds_read_b128 v[162:165], v36 offset:2048
	ds_read_b128 v[166:169], v36 offset:3072
	v_add_u32_e32 v36, s88, v160
	ds_read_b128 v[170:173], v36
	ds_read_b128 v[174:177], v36 offset:1024
	ds_read_b128 v[178:181], v36 offset:2048
	ds_read_b128 v[182:185], v36 offset:3072
	s_add_i32 m0, s19, 0xc000
	ds_read_b128 v[186:189], v161
	ds_read_b128 v[190:193], v161 offset:1024
	ds_read_b128 v[194:197], v161 offset:2048
	ds_read_b128 v[198:201], v161 offset:3072
	ds_read_b128 v[202:205], v161 offset:4096
	ds_read_b128 v[206:209], v161 offset:5120
	ds_read_b128 v[210:213], v161 offset:6144
	ds_read_b128 v[214:217], v161 offset:7168
	global_load_lds_dwordx4 v148, s[20:21]
	s_add_i32 m0, s19, 0xe000
	s_nop 0
	global_load_lds_dwordx4 v150, s[20:21]
	s_waitcnt vmcnt(8)
	s_waitcnt lgkmcnt(0)
	s_barrier
	s_setprio 1
	s_waitcnt lgkmcnt(0)
	v_mfma_f32_16x16x32_bf16 v[132:135], v[152:155], v[186:189], v[132:135]
	v_mfma_f32_16x16x32_bf16 v[128:131], v[162:165], v[186:189], v[128:131]
	v_mfma_f32_16x16x32_bf16 v[116:119], v[152:155], v[194:197], v[116:119]
	v_mfma_f32_16x16x32_bf16 v[112:115], v[162:165], v[194:197], v[112:115]
	v_mfma_f32_16x16x32_bf16 v[100:103], v[152:155], v[202:205], v[100:103]
	v_mfma_f32_16x16x32_bf16 v[96:99], v[162:165], v[202:205], v[96:99]
	v_mfma_f32_16x16x32_bf16 v[84:87], v[152:155], v[210:213], v[84:87]
	v_mfma_f32_16x16x32_bf16 v[80:83], v[162:165], v[210:213], v[80:83]
	v_mfma_f32_16x16x32_bf16 v[132:135], v[156:159], v[190:193], v[132:135]
	v_mfma_f32_16x16x32_bf16 v[128:131], v[166:169], v[190:193], v[128:131]
	v_mfma_f32_16x16x32_bf16 v[116:119], v[156:159], v[198:201], v[116:119]
	v_mfma_f32_16x16x32_bf16 v[112:115], v[166:169], v[198:201], v[112:115]
	v_mfma_f32_16x16x32_bf16 v[100:103], v[156:159], v[206:209], v[100:103]
	v_mfma_f32_16x16x32_bf16 v[96:99], v[166:169], v[206:209], v[96:99]
	v_mfma_f32_16x16x32_bf16 v[84:87], v[156:159], v[214:217], v[84:87]
	v_mfma_f32_16x16x32_bf16 v[80:83], v[166:169], v[214:217], v[80:83]
	s_setprio 0
	s_setprio 1
	v_mfma_f32_16x16x32_bf16 v[124:127], v[170:173], v[186:189], v[124:127]
	v_mfma_f32_16x16x32_bf16 v[120:123], v[178:181], v[186:189], v[120:123]
	v_mfma_f32_16x16x32_bf16 v[108:111], v[170:173], v[194:197], v[108:111]
	v_mfma_f32_16x16x32_bf16 v[104:107], v[178:181], v[194:197], v[104:107]
	v_mfma_f32_16x16x32_bf16 v[92:95], v[170:173], v[202:205], v[92:95]
	v_mfma_f32_16x16x32_bf16 v[88:91], v[178:181], v[202:205], v[88:91]
	v_mfma_f32_16x16x32_bf16 v[76:79], v[170:173], v[210:213], v[76:79]
	v_mfma_f32_16x16x32_bf16 v[72:75], v[178:181], v[210:213], v[72:75]
	v_mfma_f32_16x16x32_bf16 v[124:127], v[174:177], v[190:193], v[124:127]
	v_mfma_f32_16x16x32_bf16 v[120:123], v[182:185], v[190:193], v[120:123]
	v_mfma_f32_16x16x32_bf16 v[108:111], v[174:177], v[198:201], v[108:111]
	v_mfma_f32_16x16x32_bf16 v[104:107], v[182:185], v[198:201], v[104:107]
	v_mfma_f32_16x16x32_bf16 v[92:95], v[174:177], v[206:209], v[92:95]
	v_mfma_f32_16x16x32_bf16 v[88:91], v[182:185], v[206:209], v[88:91]
	v_mfma_f32_16x16x32_bf16 v[76:79], v[174:177], v[214:217], v[76:79]
	v_mfma_f32_16x16x32_bf16 v[72:75], v[182:185], v[214:217], v[72:75]
	s_setprio 0
	s_barrier
	s_add_i32 s13, s13, s31
	s_mov_b32 m0, s13
	ds_read_b128 v[186:189], v161 offset:16384
	ds_read_b128 v[190:193], v161 offset:17408
	ds_read_b128 v[194:197], v161 offset:18432
	ds_read_b128 v[198:201], v161 offset:19456
	ds_read_b128 v[202:205], v161 offset:20480
	ds_read_b128 v[206:209], v161 offset:21504
	ds_read_b128 v[210:213], v161 offset:22528
	ds_read_b128 v[214:217], v161 offset:23552
	global_load_lds_dwordx4 v140, s[24:25]
	s_add_i32 m0, s13, 0x2000
	s_add_u32 s68, s24, 0x4000
	s_addc_u32 s69, s25, 0
	s_add_i32 s13, s88, s31
	global_load_lds_dwordx4 v136, s[24:25]
	s_mov_b32 m0, s13
	s_nop 0
	global_load_lds_dwordx4 v140, s[68:69]
	s_add_i32 m0, s13, 0x2000
	s_nop 0
	global_load_lds_dwordx4 v136, s[68:69]
	s_mov_b32 m0, s19
	s_nop 0
	global_load_lds_dwordx4 v142, s[26:27]
	s_mov_b32 m0, s35
	s_nop 0
	global_load_lds_dwordx4 v138, s[26:27]
	s_waitcnt vmcnt(8)
	s_waitcnt lgkmcnt(0)
	s_barrier
	s_setprio 1
	s_waitcnt lgkmcnt(0)
	v_mfma_f32_16x16x32_bf16 v[68:71], v[152:155], v[186:189], v[68:71]
	v_mfma_f32_16x16x32_bf16 v[64:67], v[162:165], v[186:189], v[64:67]
	v_mfma_f32_16x16x32_bf16 v[52:55], v[152:155], v[194:197], v[52:55]
	v_mfma_f32_16x16x32_bf16 v[48:51], v[162:165], v[194:197], v[48:51]
	v_mfma_f32_16x16x32_bf16 v[32:35], v[152:155], v[202:205], v[32:35]
	v_mfma_f32_16x16x32_bf16 v[28:31], v[162:165], v[202:205], v[28:31]
	v_mfma_f32_16x16x32_bf16 v[16:19], v[152:155], v[210:213], v[16:19]
	v_mfma_f32_16x16x32_bf16 v[12:15], v[162:165], v[210:213], v[12:15]
	v_mfma_f32_16x16x32_bf16 v[68:71], v[156:159], v[190:193], v[68:71]
	v_mfma_f32_16x16x32_bf16 v[64:67], v[166:169], v[190:193], v[64:67]
	v_mfma_f32_16x16x32_bf16 v[52:55], v[156:159], v[198:201], v[52:55]
	v_mfma_f32_16x16x32_bf16 v[48:51], v[166:169], v[198:201], v[48:51]
	v_mfma_f32_16x16x32_bf16 v[32:35], v[156:159], v[206:209], v[32:35]
	v_mfma_f32_16x16x32_bf16 v[28:31], v[166:169], v[206:209], v[28:31]
	v_mfma_f32_16x16x32_bf16 v[16:19], v[156:159], v[214:217], v[16:19]
	v_mfma_f32_16x16x32_bf16 v[12:15], v[166:169], v[214:217], v[12:15]
	s_setprio 0
	s_setprio 1
	v_mfma_f32_16x16x32_bf16 v[60:63], v[170:173], v[186:189], v[60:63]
	v_mfma_f32_16x16x32_bf16 v[56:59], v[178:181], v[186:189], v[56:59]
	v_mfma_f32_16x16x32_bf16 v[44:47], v[170:173], v[194:197], v[44:47]
	v_mfma_f32_16x16x32_bf16 v[40:43], v[178:181], v[194:197], v[40:43]
	v_mfma_f32_16x16x32_bf16 v[24:27], v[170:173], v[202:205], v[24:27]
	v_mfma_f32_16x16x32_bf16 v[20:23], v[178:181], v[202:205], v[20:23]
	v_mfma_f32_16x16x32_bf16 v[8:11], v[170:173], v[210:213], v[8:11]
	v_mfma_f32_16x16x32_bf16 v[4:7], v[178:181], v[210:213], v[4:7]
	v_mfma_f32_16x16x32_bf16 v[60:63], v[174:177], v[190:193], v[60:63]
	v_mfma_f32_16x16x32_bf16 v[56:59], v[182:185], v[190:193], v[56:59]
	v_mfma_f32_16x16x32_bf16 v[44:47], v[174:177], v[198:201], v[44:47]
	v_mfma_f32_16x16x32_bf16 v[40:43], v[182:185], v[198:201], v[40:43]
	v_mfma_f32_16x16x32_bf16 v[24:27], v[174:177], v[206:209], v[24:27]
	v_mfma_f32_16x16x32_bf16 v[20:23], v[182:185], v[206:209], v[20:23]
	v_mfma_f32_16x16x32_bf16 v[8:11], v[174:177], v[214:217], v[8:11]
	v_mfma_f32_16x16x32_bf16 v[4:7], v[182:185], v[214:217], v[4:7]
	s_setprio 0
	s_barrier
; #define PG8_STAGE(bufoff, gbase, voff) do { _Pragma("unroll") for (int _i = 0; _i < 2; ++_i) \
;         __builtin_amdgcn_global_load_lds((const unsigned*)((const char*)(gbase) + (voff)[_i]), (PG8_LAS unsigned*)(lds + (bufoff) + ldsw + _i * 8192), 16, 0, 0); } while (0)
; #define PG8_LDA(dst, b, h) do { _Pragma("unroll") for (int m = 0; m < 4; ++m) _Pragma("unroll") for (int k = 0; k < 2; ++k) dst[m][k] = *(const PG8_LAS bf16x8*)(lds + PG8_SA(b, h) + aoff + m * 2048 + k * 1024); } while (0)
; #define PG8_LDB(dst, b, h) do { _Pragma("unroll") for (int n = 0; n < 2; ++n) _Pragma("unroll") for (int k = 0; k < 2; ++k) dst[n][k] = *(const PG8_LAS bf16x8*)(lds + PG8_SB(b, h) + boff + n * 2048 + k * 1024); } while (0)
; #define PG8_MMA(ai, bj, At, Bt) do { __builtin_amdgcn_s_setprio(1); _Pragma("unroll") for (int m = 0; m < 4; ++m) _Pragma("unroll") for (int n = 0; n < 2; ++n) _Pragma("unroll") for (int k = 0; k < 2; ++k) \
;         acc[ai][bj][m][n] = __builtin_amdgcn_mfma_f32_16x16x32_bf16(Bt[n][k], At[m][k], acc[ai][bj][m][n], 0, 0, 0); __builtin_amdgcn_s_setprio(0); } while (0)
; #define PG8_WAIT_V(n) asm volatile("s_waitcnt vmcnt(" #n ")" ::: "memory")
; #define PG8_WAIT_L(n) asm volatile("s_waitcnt lgkmcnt(" #n ")" ::: "memory")
; #define PG8_BAR __builtin_amdgcn_s_barrier()
; #define PG8_SCHED __builtin_amdgcn_sched_barrier(0)
; template <class Epi, class Sched, bool ALIGN_EPI = false, bool SP2 = false, bool ABLK = false, bool BBLK = false>
; __device__ __forceinline__ void gemm_phase(PG8_LAS unsigned char* lds, const Gemm g, const Sched& S, const Epi& E) {
;     ...
;             PG8_LDB(B0, 1, 0); PG8_LDB(B1, 1, 1); PG8_SCHED; PG8_LDA(At, 1, 0); PG8_STAGE(PG8_SA(0, 1), a2 + hstepA, voffA);
;             PG8_WAIT_V(8); PG8_WAIT_L(0); PG8_BAR; PG8_MMA(0, 0, At, B0); PG8_MMA(0, 1, At, B1); PG8_BAR; PG8_SCHED;
;             PG8_LDA(At, 1, 1); PG8_STAGE(PG8_SB(1, 0), b3, voffB); PG8_STAGE(PG8_SB(1, 1), b3 + hstepB, voffB); PG8_STAGE(PG8_SA(1, 0), a3, voffA);
;             PG8_WAIT_V(8); PG8_WAIT_L(0); PG8_BAR; PG8_MMA(1, 0, At, B0); PG8_MMA(1, 1, At, B1); PG8_BAR; PG8_SCHED;
	s_add_i32 s13, 0, 0x18000
	v_add_u32_e32 v36, s13, v160
	s_add_i32 s68, 0, 0x1c000
	ds_read_b128 v[152:155], v36
	ds_read_b128 v[156:159], v36 offset:1024
	ds_read_b128 v[162:165], v36 offset:2048
	ds_read_b128 v[166:169], v36 offset:3072
	v_add_u32_e32 v36, s68, v160
	ds_read_b128 v[170:173], v36
	ds_read_b128 v[174:177], v36 offset:1024
	ds_read_b128 v[178:181], v36 offset:2048
	ds_read_b128 v[182:185], v36 offset:3072
	s_add_u32 s26, s26, 0x4000
	s_addc_u32 s27, s27, 0
	s_mov_b32 m0, s36
	ds_read_b128 v[186:189], v161 offset:32768
	ds_read_b128 v[190:193], v161 offset:33792
	ds_read_b128 v[194:197], v161 offset:34816
	ds_read_b128 v[198:201], v161 offset:35840
	ds_read_b128 v[202:205], v161 offset:36864
	ds_read_b128 v[206:209], v161 offset:37888
	ds_read_b128 v[210:213], v161 offset:38912
	ds_read_b128 v[214:217], v161 offset:39936
	global_load_lds_dwordx4 v142, s[26:27]
	s_mov_b32 m0, s37
	s_nop 0
	global_load_lds_dwordx4 v138, s[26:27]
	s_waitcnt vmcnt(8)
	s_waitcnt lgkmcnt(0)
	s_barrier
	s_setprio 1
	s_waitcnt lgkmcnt(0)
	v_mfma_f32_16x16x32_bf16 v[132:135], v[152:155], v[186:189], v[132:135]
	v_mfma_f32_16x16x32_bf16 v[128:131], v[162:165], v[186:189], v[128:131]
	v_mfma_f32_16x16x32_bf16 v[116:119], v[152:155], v[194:197], v[116:119]
	v_mfma_f32_16x16x32_bf16 v[112:115], v[162:165], v[194:197], v[112:115]
	v_mfma_f32_16x16x32_bf16 v[100:103], v[152:155], v[202:205], v[100:103]
	v_mfma_f32_16x16x32_bf16 v[96:99], v[162:165], v[202:205], v[96:99]
	v_mfma_f32_16x16x32_bf16 v[84:87], v[152:155], v[210:213], v[84:87]
	v_mfma_f32_16x16x32_bf16 v[80:83], v[162:165], v[210:213], v[80:83]
	v_mfma_f32_16x16x32_bf16 v[132:135], v[156:159], v[190:193], v[132:135]
	v_mfma_f32_16x16x32_bf16 v[128:131], v[166:169], v[190:193], v[128:131]
	v_mfma_f32_16x16x32_bf16 v[116:119], v[156:159], v[198:201], v[116:119]
	v_mfma_f32_16x16x32_bf16 v[112:115], v[166:169], v[198:201], v[112:115]
	v_mfma_f32_16x16x32_bf16 v[100:103], v[156:159], v[206:209], v[100:103]
	v_mfma_f32_16x16x32_bf16 v[96:99], v[166:169], v[206:209], v[96:99]
	v_mfma_f32_16x16x32_bf16 v[84:87], v[156:159], v[214:217], v[84:87]
	v_mfma_f32_16x16x32_bf16 v[80:83], v[166:169], v[214:217], v[80:83]
	s_setprio 0
	s_setprio 1
	v_mfma_f32_16x16x32_bf16 v[124:127], v[170:173], v[186:189], v[124:127]
	v_mfma_f32_16x16x32_bf16 v[120:123], v[178:181], v[186:189], v[120:123]
	v_mfma_f32_16x16x32_bf16 v[108:111], v[170:173], v[194:197], v[108:111]
	v_mfma_f32_16x16x32_bf16 v[104:107], v[178:181], v[194:197], v[104:107]
	v_mfma_f32_16x16x32_bf16 v[92:95], v[170:173], v[202:205], v[92:95]
	v_mfma_f32_16x16x32_bf16 v[88:91], v[178:181], v[202:205], v[88:91]
	v_mfma_f32_16x16x32_bf16 v[76:79], v[170:173], v[210:213], v[76:79]
	v_mfma_f32_16x16x32_bf16 v[72:75], v[178:181], v[210:213], v[72:75]
	v_mfma_f32_16x16x32_bf16 v[124:127], v[174:177], v[190:193], v[124:127]
	v_mfma_f32_16x16x32_bf16 v[120:123], v[182:185], v[190:193], v[120:123]
	v_mfma_f32_16x16x32_bf16 v[108:111], v[174:177], v[198:201], v[108:111]
	v_mfma_f32_16x16x32_bf16 v[104:107], v[182:185], v[198:201], v[104:107]
	v_mfma_f32_16x16x32_bf16 v[92:95], v[174:177], v[206:209], v[92:95]
	v_mfma_f32_16x16x32_bf16 v[88:91], v[182:185], v[206:209], v[88:91]
	v_mfma_f32_16x16x32_bf16 v[76:79], v[174:177], v[214:217], v[76:79]
	v_mfma_f32_16x16x32_bf16 v[72:75], v[182:185], v[214:217], v[72:75]
	s_setprio 0
	s_barrier
	s_add_u32 s26, s24, 0x8000
	s_addc_u32 s27, s25, 0
	s_add_i32 s13, s13, s31
	s_mov_b32 m0, s13
	ds_read_b128 v[186:189], v161 offset:49152
	ds_read_b128 v[190:193], v161 offset:50176
	ds_read_b128 v[194:197], v161 offset:51200
	ds_read_b128 v[198:201], v161 offset:52224
	ds_read_b128 v[202:205], v161 offset:53248
	ds_read_b128 v[206:209], v161 offset:54272
	ds_read_b128 v[210:213], v161 offset:55296
	ds_read_b128 v[214:217], v161 offset:56320
	global_load_lds_dwordx4 v140, s[26:27]
	s_add_i32 m0, s13, 0x2000
	s_add_u32 s24, s24, 0xc000
	s_addc_u32 s25, s25, 0
	s_add_i32 s13, s68, s31
	global_load_lds_dwordx4 v136, s[26:27]
	s_mov_b32 m0, s13
	s_nop 0
	global_load_lds_dwordx4 v140, s[24:25]
	s_add_i32 m0, s13, 0x2000
	s_nop 0
	global_load_lds_dwordx4 v136, s[24:25]
	s_mov_b32 m0, s62
	s_nop 0
	global_load_lds_dwordx4 v142, s[22:23]
	s_mov_b32 m0, s63
	s_nop 0
	global_load_lds_dwordx4 v138, s[22:23]
	s_waitcnt vmcnt(8)
	s_waitcnt lgkmcnt(0)
	s_barrier
	s_setprio 1
	s_waitcnt lgkmcnt(0)
	v_mfma_f32_16x16x32_bf16 v[68:71], v[152:155], v[186:189], v[68:71]
	v_mfma_f32_16x16x32_bf16 v[64:67], v[162:165], v[186:189], v[64:67]
	v_mfma_f32_16x16x32_bf16 v[52:55], v[152:155], v[194:197], v[52:55]
	v_mfma_f32_16x16x32_bf16 v[48:51], v[162:165], v[194:197], v[48:51]
	v_mfma_f32_16x16x32_bf16 v[32:35], v[152:155], v[202:205], v[32:35]
	v_mfma_f32_16x16x32_bf16 v[28:31], v[162:165], v[202:205], v[28:31]
	v_mfma_f32_16x16x32_bf16 v[16:19], v[152:155], v[210:213], v[16:19]
	v_mfma_f32_16x16x32_bf16 v[12:15], v[162:165], v[210:213], v[12:15]
	v_mfma_f32_16x16x32_bf16 v[68:71], v[156:159], v[190:193], v[68:71]
	v_mfma_f32_16x16x32_bf16 v[64:67], v[166:169], v[190:193], v[64:67]
	v_mfma_f32_16x16x32_bf16 v[52:55], v[156:159], v[198:201], v[52:55]
	v_mfma_f32_16x16x32_bf16 v[48:51], v[166:169], v[198:201], v[48:51]
	v_mfma_f32_16x16x32_bf16 v[32:35], v[156:159], v[206:209], v[32:35]
	v_mfma_f32_16x16x32_bf16 v[28:31], v[166:169], v[206:209], v[28:31]
	v_mfma_f32_16x16x32_bf16 v[16:19], v[156:159], v[214:217], v[16:19]
	v_mfma_f32_16x16x32_bf16 v[12:15], v[166:169], v[214:217], v[12:15]
	s_setprio 0
	s_setprio 1
	v_mfma_f32_16x16x32_bf16 v[60:63], v[170:173], v[186:189], v[60:63]
	v_mfma_f32_16x16x32_bf16 v[56:59], v[178:181], v[186:189], v[56:59]
	v_mfma_f32_16x16x32_bf16 v[44:47], v[170:173], v[194:197], v[44:47]
	v_mfma_f32_16x16x32_bf16 v[40:43], v[178:181], v[194:197], v[40:43]
	v_mfma_f32_16x16x32_bf16 v[24:27], v[170:173], v[202:205], v[24:27]
	v_mfma_f32_16x16x32_bf16 v[20:23], v[178:181], v[202:205], v[20:23]
	v_mfma_f32_16x16x32_bf16 v[8:11], v[170:173], v[210:213], v[8:11]
	v_mfma_f32_16x16x32_bf16 v[4:7], v[178:181], v[210:213], v[4:7]
	v_mfma_f32_16x16x32_bf16 v[60:63], v[174:177], v[190:193], v[60:63]
	v_mfma_f32_16x16x32_bf16 v[56:59], v[182:185], v[190:193], v[56:59]
	v_mfma_f32_16x16x32_bf16 v[44:47], v[174:177], v[198:201], v[44:47]
	v_mfma_f32_16x16x32_bf16 v[40:43], v[182:185], v[198:201], v[40:43]
	v_mfma_f32_16x16x32_bf16 v[24:27], v[174:177], v[206:209], v[24:27]
	v_mfma_f32_16x16x32_bf16 v[20:23], v[182:185], v[206:209], v[20:23]
	v_mfma_f32_16x16x32_bf16 v[8:11], v[174:177], v[214:217], v[8:11]
	v_mfma_f32_16x16x32_bf16 v[4:7], v[182:185], v[214:217], v[4:7]
	s_setprio 0
	s_barrier
	s_add_i32 vcc_hi, vcc_hi, 2
	s_add_u32 s20, s20, 0x10000
	s_addc_u32 s21, s21, 0
	s_add_u32 s77, s77, 0x10000
	s_addc_u32 vcc_lo, vcc_lo, 0
	s_cmp_gt_u32 vcc_hi, 29
	s_cbranch_scc0 .LBB0_185
	s_and_b64 vcc, exec, s[4:5]
	s_cbranch_vccz .LBB0_188
	s_barrier

; #define PG8_STAGE(bufoff, gbase, voff) do { _Pragma("unroll") for (int _i = 0; _i < 2; ++_i) \
;         __builtin_amdgcn_global_load_lds((const unsigned*)((const char*)(gbase) + (voff)[_i]), (PG8_LAS unsigned*)(lds + (bufoff) + ldsw + _i * 8192), 16, 0, 0); } while (0)
; #define PG8_LDA(dst, b, h) do { _Pragma("unroll") for (int m = 0; m < 4; ++m) _Pragma("unroll") for (int k = 0; k < 2; ++k) dst[m][k] = *(const PG8_LAS bf16x8*)(lds + PG8_SA(b, h) + aoff + m * 2048 + k * 1024); } while (0)
; #define PG8_LDB(dst, b, h) do { _Pragma("unroll") for (int n = 0; n < 2; ++n) _Pragma("unroll") for (int k = 0; k < 2; ++k) dst[n][k] = *(const PG8_LAS bf16x8*)(lds + PG8_SB(b, h) + boff + n * 2048 + k * 1024); } while (0)
; #define PG8_MMA(ai, bj, At, Bt) do { __builtin_amdgcn_s_setprio(1); _Pragma("unroll") for (int m = 0; m < 4; ++m) _Pragma("unroll") for (int n = 0; n < 2; ++n) _Pragma("unroll") for (int k = 0; k < 2; ++k) \
;         acc[ai][bj][m][n] = __builtin_amdgcn_mfma_f32_16x16x32_bf16(Bt[n][k], At[m][k], acc[ai][bj][m][n], 0, 0, 0); __builtin_amdgcn_s_setprio(0); } while (0)
; #define PG8_WAIT_V(n) asm volatile("s_waitcnt vmcnt(" #n ")" ::: "memory")
; template <class Epi, class Sched, bool ALIGN_EPI = false, bool SP2 = false, bool ABLK = false, bool BBLK = false>
; __device__ __forceinline__ void gemm_phase(PG8_LAS unsigned char* lds, const Gemm g, const Sched& S, const Epi& E) {
;     ...
;         for (int t = 0; t < nt; t += 2) {
;             const bool last = (t == nt - 2);
;             const char* a1 = cA + (size_t)(t + 1) * kstepA;
;             const char* a2 = last ? nA : cA + (size_t)(t + 2) * kstepA; const char* b2 = last ? nB : cB + (size_t)(t + 2) * kstepB;
;             const char* a3 = a2 + kstepA; const char* b3 = b2 + kstepB;
;             if (last && has_next) S.a_ready(nxt);
;             if constexpr (SP2) {
;             PG8_LDB(B0, 0, 0); PG8_LDB(B1, 0, 1); PG8_SCHED; PG8_LDA(At, 0, 0); PG8_STAGE(PG8_SA(1, 1), a1 + hstepA, voffA);
;             PG8_WAIT_V(8); PG8_WAIT_L(0); PG8_BAR; PG8_MMA(0, 0, At, B0); PG8_MMA(0, 1, At, B1); PG8_BAR; PG8_SCHED;
;             PG8_LDA(At, 0, 1); PG8_STAGE(PG8_SB(0, 0), b2, voffB); PG8_STAGE(PG8_SB(0, 1), b2 + hstepB, voffB); PG8_STAGE(PG8_SA(0, 0), a2, voffA);
;             PG8_WAIT_V(8); PG8_WAIT_L(0); PG8_BAR; PG8_MMA(1, 0, At, B0); PG8_MMA(1, 1, At, B1); PG8_BAR; PG8_SCHED;
.LBB0_439:
	s_add_u32 s16, s10, 0x4000
	s_addc_u32 s17, s11, 0
	s_cmpk_eq_i32 s13, 0x54
	s_cselect_b32 s20, s0, s16
	s_cselect_b32 s21, s1, s17
	s_cselect_b32 s18, s8, vcc_lo
	s_cselect_b32 s19, s9, vcc_hi
	s_add_u32 s16, s20, 0x8000
	s_addc_u32 s17, s21, 0
	s_add_i32 s68, 0, 0x10000
	v_add_u32_e32 v36, s68, v148
	s_add_i32 s88, 0, 0x14000
	ds_read_b128 v[152:155], v36
	ds_read_b128 v[156:159], v36 offset:1024
	ds_read_b128 v[160:163], v36 offset:2048
	ds_read_b128 v[164:167], v36 offset:3072
	v_add_u32_e32 v36, s88, v148
	ds_read_b128 v[168:171], v36
	ds_read_b128 v[172:175], v36 offset:1024
	ds_read_b128 v[176:179], v36 offset:2048
	ds_read_b128 v[180:183], v36 offset:3072
	s_add_i32 m0, s27, 0xc000
	ds_read_b128 v[184:187], v150
	ds_read_b128 v[188:191], v150 offset:1024
	ds_read_b128 v[192:195], v150 offset:2048
	ds_read_b128 v[196:199], v150 offset:3072
	ds_read_b128 v[200:203], v150 offset:4096
	ds_read_b128 v[204:207], v150 offset:5120
	ds_read_b128 v[208:211], v150 offset:6144
	ds_read_b128 v[212:215], v150 offset:7168
	global_load_lds_dwordx4 v144, s[10:11]
	s_add_i32 m0, s27, 0xe000
	s_nop 0
	global_load_lds_dwordx4 v146, s[10:11]
	s_waitcnt vmcnt(8)
	s_waitcnt lgkmcnt(0)
	s_barrier
	s_setprio 1
	s_waitcnt lgkmcnt(0)
	v_mfma_f32_16x16x32_bf16 v[132:135], v[152:155], v[184:187], v[132:135]
	v_mfma_f32_16x16x32_bf16 v[128:131], v[160:163], v[184:187], v[128:131]
	v_mfma_f32_16x16x32_bf16 v[124:127], v[152:155], v[192:195], v[124:127]
	v_mfma_f32_16x16x32_bf16 v[120:123], v[160:163], v[192:195], v[120:123]
	v_mfma_f32_16x16x32_bf16 v[108:111], v[152:155], v[200:203], v[108:111]
	v_mfma_f32_16x16x32_bf16 v[104:107], v[160:163], v[200:203], v[104:107]
	v_mfma_f32_16x16x32_bf16 v[92:95], v[152:155], v[208:211], v[92:95]
	v_mfma_f32_16x16x32_bf16 v[88:91], v[160:163], v[208:211], v[88:91]
	v_mfma_f32_16x16x32_bf16 v[132:135], v[156:159], v[188:191], v[132:135]
	v_mfma_f32_16x16x32_bf16 v[128:131], v[164:167], v[188:191], v[128:131]
	v_mfma_f32_16x16x32_bf16 v[124:127], v[156:159], v[196:199], v[124:127]
	v_mfma_f32_16x16x32_bf16 v[120:123], v[164:167], v[196:199], v[120:123]
	v_mfma_f32_16x16x32_bf16 v[108:111], v[156:159], v[204:207], v[108:111]
	v_mfma_f32_16x16x32_bf16 v[104:107], v[164:167], v[204:207], v[104:107]
	v_mfma_f32_16x16x32_bf16 v[92:95], v[156:159], v[212:215], v[92:95]
	v_mfma_f32_16x16x32_bf16 v[88:91], v[164:167], v[212:215], v[88:91]
	s_setprio 0
	s_setprio 1
	v_mfma_f32_16x16x32_bf16 v[116:119], v[168:171], v[184:187], v[116:119]
	v_mfma_f32_16x16x32_bf16 v[112:115], v[176:179], v[184:187], v[112:115]
	v_mfma_f32_16x16x32_bf16 v[100:103], v[168:171], v[192:195], v[100:103]
	v_mfma_f32_16x16x32_bf16 v[96:99], v[176:179], v[192:195], v[96:99]
	v_mfma_f32_16x16x32_bf16 v[84:87], v[168:171], v[200:203], v[84:87]
	v_mfma_f32_16x16x32_bf16 v[80:83], v[176:179], v[200:203], v[80:83]
	v_mfma_f32_16x16x32_bf16 v[76:79], v[168:171], v[208:211], v[76:79]
	v_mfma_f32_16x16x32_bf16 v[72:75], v[176:179], v[208:211], v[72:75]
	v_mfma_f32_16x16x32_bf16 v[116:119], v[172:175], v[188:191], v[116:119]
	v_mfma_f32_16x16x32_bf16 v[112:115], v[180:183], v[188:191], v[112:115]
	v_mfma_f32_16x16x32_bf16 v[100:103], v[172:175], v[196:199], v[100:103]
	v_mfma_f32_16x16x32_bf16 v[96:99], v[180:183], v[196:199], v[96:99]
	v_mfma_f32_16x16x32_bf16 v[84:87], v[172:175], v[204:207], v[84:87]
	v_mfma_f32_16x16x32_bf16 v[80:83], v[180:183], v[204:207], v[80:83]
	v_mfma_f32_16x16x32_bf16 v[76:79], v[172:175], v[212:215], v[76:79]
	v_mfma_f32_16x16x32_bf16 v[72:75], v[180:183], v[212:215], v[72:75]
	s_setprio 0
	s_barrier
	s_add_i32 s68, s68, s24
	s_mov_b32 m0, s68
	ds_read_b128 v[184:187], v150 offset:16384
	ds_read_b128 v[188:191], v150 offset:17408
	ds_read_b128 v[192:195], v150 offset:18432
	ds_read_b128 v[196:199], v150 offset:19456
	ds_read_b128 v[200:203], v150 offset:20480
	ds_read_b128 v[204:207], v150 offset:21504
	ds_read_b128 v[208:211], v150 offset:22528
	ds_read_b128 v[212:215], v150 offset:23552
	global_load_lds_dwordx4 v138, s[18:19]
	s_add_i32 m0, s68, 0x2000
	s_add_u32 s68, s18, 0x4000
	s_addc_u32 s69, s19, 0
	s_add_i32 s88, s88, s24
	global_load_lds_dwordx4 v142, s[18:19]
	s_mov_b32 m0, s88
	s_nop 0
	global_load_lds_dwordx4 v138, s[68:69]
	s_add_i32 m0, s88, 0x2000
	s_nop 0
	global_load_lds_dwordx4 v142, s[68:69]
	s_mov_b32 m0, s27
	s_nop 0
	global_load_lds_dwordx4 v136, s[20:21]
	s_mov_b32 m0, s28
	s_nop 0
	global_load_lds_dwordx4 v140, s[20:21]
	s_waitcnt vmcnt(8)
	s_waitcnt lgkmcnt(0)
	s_barrier
	s_setprio 1
	s_waitcnt lgkmcnt(0)
	v_mfma_f32_16x16x32_bf16 v[68:71], v[152:155], v[184:187], v[68:71]
	v_mfma_f32_16x16x32_bf16 v[64:67], v[160:163], v[184:187], v[64:67]
	v_mfma_f32_16x16x32_bf16 v[60:63], v[152:155], v[192:195], v[60:63]
	v_mfma_f32_16x16x32_bf16 v[56:59], v[160:163], v[192:195], v[56:59]
	v_mfma_f32_16x16x32_bf16 v[44:47], v[152:155], v[200:203], v[44:47]
	v_mfma_f32_16x16x32_bf16 v[40:43], v[160:163], v[200:203], v[40:43]
	v_mfma_f32_16x16x32_bf16 v[24:27], v[152:155], v[208:211], v[24:27]
	v_mfma_f32_16x16x32_bf16 v[20:23], v[160:163], v[208:211], v[20:23]
	v_mfma_f32_16x16x32_bf16 v[68:71], v[156:159], v[188:191], v[68:71]
	v_mfma_f32_16x16x32_bf16 v[64:67], v[164:167], v[188:191], v[64:67]
	v_mfma_f32_16x16x32_bf16 v[60:63], v[156:159], v[196:199], v[60:63]
	v_mfma_f32_16x16x32_bf16 v[56:59], v[164:167], v[196:199], v[56:59]
	v_mfma_f32_16x16x32_bf16 v[44:47], v[156:159], v[204:207], v[44:47]
	v_mfma_f32_16x16x32_bf16 v[40:43], v[164:167], v[204:207], v[40:43]
	v_mfma_f32_16x16x32_bf16 v[24:27], v[156:159], v[212:215], v[24:27]
	v_mfma_f32_16x16x32_bf16 v[20:23], v[164:167], v[212:215], v[20:23]
	s_setprio 0
	s_setprio 1
	v_mfma_f32_16x16x32_bf16 v[52:55], v[168:171], v[184:187], v[52:55]
	v_mfma_f32_16x16x32_bf16 v[48:51], v[176:179], v[184:187], v[48:51]
	v_mfma_f32_16x16x32_bf16 v[32:35], v[168:171], v[192:195], v[32:35]
	v_mfma_f32_16x16x32_bf16 v[28:31], v[176:179], v[192:195], v[28:31]
	v_mfma_f32_16x16x32_bf16 v[16:19], v[168:171], v[200:203], v[16:19]
	v_mfma_f32_16x16x32_bf16 v[12:15], v[176:179], v[200:203], v[12:15]
	v_mfma_f32_16x16x32_bf16 v[8:11], v[168:171], v[208:211], v[8:11]
	v_mfma_f32_16x16x32_bf16 v[4:7], v[176:179], v[208:211], v[4:7]
	v_mfma_f32_16x16x32_bf16 v[52:55], v[172:175], v[188:191], v[52:55]
	v_mfma_f32_16x16x32_bf16 v[48:51], v[180:183], v[188:191], v[48:51]
	v_mfma_f32_16x16x32_bf16 v[32:35], v[172:175], v[196:199], v[32:35]
	v_mfma_f32_16x16x32_bf16 v[28:31], v[180:183], v[196:199], v[28:31]
	v_mfma_f32_16x16x32_bf16 v[16:19], v[172:175], v[204:207], v[16:19]
	v_mfma_f32_16x16x32_bf16 v[12:15], v[180:183], v[204:207], v[12:15]
	v_mfma_f32_16x16x32_bf16 v[8:11], v[172:175], v[212:215], v[8:11]
	v_mfma_f32_16x16x32_bf16 v[4:7], v[180:183], v[212:215], v[4:7]
	s_setprio 0
	s_barrier
; #define PG8_STAGE(bufoff, gbase, voff) do { _Pragma("unroll") for (int _i = 0; _i < 2; ++_i) \
;         __builtin_amdgcn_global_load_lds((const unsigned*)((const char*)(gbase) + (voff)[_i]), (PG8_LAS unsigned*)(lds + (bufoff) + ldsw + _i * 8192), 16, 0, 0); } while (0)
; #define PG8_LDA(dst, b, h) do { _Pragma("unroll") for (int m = 0; m < 4; ++m) _Pragma("unroll") for (int k = 0; k < 2; ++k) dst[m][k] = *(const PG8_LAS bf16x8*)(lds + PG8_SA(b, h) + aoff + m * 2048 + k * 1024); } while (0)
; #define PG8_LDB(dst, b, h) do { _Pragma("unroll") for (int n = 0; n < 2; ++n) _Pragma("unroll") for (int k = 0; k < 2; ++k) dst[n][k] = *(const PG8_LAS bf16x8*)(lds + PG8_SB(b, h) + boff + n * 2048 + k * 1024); } while (0)
; #define PG8_MMA(ai, bj, At, Bt) do { __builtin_amdgcn_s_setprio(1); _Pragma("unroll") for (int m = 0; m < 4; ++m) _Pragma("unroll") for (int n = 0; n < 2; ++n) _Pragma("unroll") for (int k = 0; k < 2; ++k) \
;         acc[ai][bj][m][n] = __builtin_amdgcn_mfma_f32_16x16x32_bf16(Bt[n][k], At[m][k], acc[ai][bj][m][n], 0, 0, 0); __builtin_amdgcn_s_setprio(0); } while (0)
; #define PG8_WAIT_V(n) asm volatile("s_waitcnt vmcnt(" #n ")" ::: "memory")
; #define PG8_WAIT_L(n) asm volatile("s_waitcnt lgkmcnt(" #n ")" ::: "memory")
; #define PG8_BAR __builtin_amdgcn_s_barrier()
; #define PG8_SCHED __builtin_amdgcn_sched_barrier(0)
; template <class Epi, class Sched, bool ALIGN_EPI = false, bool SP2 = false, bool ABLK = false, bool BBLK = false>
; __device__ __forceinline__ void gemm_phase(PG8_LAS unsigned char* lds, const Gemm g, const Sched& S, const Epi& E) {
;     ...
;             PG8_LDB(B0, 1, 0); PG8_LDB(B1, 1, 1); PG8_SCHED; PG8_LDA(At, 1, 0); PG8_STAGE(PG8_SA(0, 1), a2 + hstepA, voffA);
;             PG8_WAIT_V(8); PG8_WAIT_L(0); PG8_BAR; PG8_MMA(0, 0, At, B0); PG8_MMA(0, 1, At, B1); PG8_BAR; PG8_SCHED;
;             PG8_LDA(At, 1, 1); PG8_STAGE(PG8_SB(1, 0), b3, voffB); PG8_STAGE(PG8_SB(1, 1), b3 + hstepB, voffB); PG8_STAGE(PG8_SA(1, 0), a3, voffA);
;             PG8_WAIT_V(8); PG8_WAIT_L(0); PG8_BAR; PG8_MMA(1, 0, At, B0); PG8_MMA(1, 1, At, B1); PG8_BAR; PG8_SCHED;
	s_add_i32 s68, 0, 0x18000
	v_add_u32_e32 v36, s68, v148
	s_add_i32 s69, 0, 0x1c000
	ds_read_b128 v[152:155], v36
	ds_read_b128 v[156:159], v36 offset:1024
	ds_read_b128 v[160:163], v36 offset:2048
	ds_read_b128 v[164:167], v36 offset:3072
	v_add_u32_e32 v36, s69, v148
	ds_read_b128 v[168:171], v36
	ds_read_b128 v[172:175], v36 offset:1024
	ds_read_b128 v[176:179], v36 offset:2048
	ds_read_b128 v[180:183], v36 offset:3072
	s_add_u32 s20, s20, 0x4000
	s_addc_u32 s21, s21, 0
	s_mov_b32 m0, s29
	ds_read_b128 v[184:187], v150 offset:32768
	ds_read_b128 v[188:191], v150 offset:33792
	ds_read_b128 v[192:195], v150 offset:34816
	ds_read_b128 v[196:199], v150 offset:35840
	ds_read_b128 v[200:203], v150 offset:36864
	ds_read_b128 v[204:207], v150 offset:37888
	ds_read_b128 v[208:211], v150 offset:38912
	ds_read_b128 v[212:215], v150 offset:39936
	global_load_lds_dwordx4 v136, s[20:21]
	s_mov_b32 m0, s30
	s_nop 0
	global_load_lds_dwordx4 v140, s[20:21]
	s_waitcnt vmcnt(8)
	s_waitcnt lgkmcnt(0)
	s_barrier
	s_setprio 1
	s_waitcnt lgkmcnt(0)
	v_mfma_f32_16x16x32_bf16 v[132:135], v[152:155], v[184:187], v[132:135]
	v_mfma_f32_16x16x32_bf16 v[128:131], v[160:163], v[184:187], v[128:131]
	v_mfma_f32_16x16x32_bf16 v[124:127], v[152:155], v[192:195], v[124:127]
	v_mfma_f32_16x16x32_bf16 v[120:123], v[160:163], v[192:195], v[120:123]
	v_mfma_f32_16x16x32_bf16 v[108:111], v[152:155], v[200:203], v[108:111]
	v_mfma_f32_16x16x32_bf16 v[104:107], v[160:163], v[200:203], v[104:107]
	v_mfma_f32_16x16x32_bf16 v[92:95], v[152:155], v[208:211], v[92:95]
	v_mfma_f32_16x16x32_bf16 v[88:91], v[160:163], v[208:211], v[88:91]
	v_mfma_f32_16x16x32_bf16 v[132:135], v[156:159], v[188:191], v[132:135]
	v_mfma_f32_16x16x32_bf16 v[128:131], v[164:167], v[188:191], v[128:131]
	v_mfma_f32_16x16x32_bf16 v[124:127], v[156:159], v[196:199], v[124:127]
	v_mfma_f32_16x16x32_bf16 v[120:123], v[164:167], v[196:199], v[120:123]
	v_mfma_f32_16x16x32_bf16 v[108:111], v[156:159], v[204:207], v[108:111]
	v_mfma_f32_16x16x32_bf16 v[104:107], v[164:167], v[204:207], v[104:107]
	v_mfma_f32_16x16x32_bf16 v[92:95], v[156:159], v[212:215], v[92:95]
	v_mfma_f32_16x16x32_bf16 v[88:91], v[164:167], v[212:215], v[88:91]
	s_setprio 0
	s_setprio 1
	v_mfma_f32_16x16x32_bf16 v[116:119], v[168:171], v[184:187], v[116:119]
	v_mfma_f32_16x16x32_bf16 v[112:115], v[176:179], v[184:187], v[112:115]
	v_mfma_f32_16x16x32_bf16 v[100:103], v[168:171], v[192:195], v[100:103]
	v_mfma_f32_16x16x32_bf16 v[96:99], v[176:179], v[192:195], v[96:99]
	v_mfma_f32_16x16x32_bf16 v[84:87], v[168:171], v[200:203], v[84:87]
	v_mfma_f32_16x16x32_bf16 v[80:83], v[176:179], v[200:203], v[80:83]
	v_mfma_f32_16x16x32_bf16 v[76:79], v[168:171], v[208:211], v[76:79]
	v_mfma_f32_16x16x32_bf16 v[72:75], v[176:179], v[208:211], v[72:75]
	v_mfma_f32_16x16x32_bf16 v[116:119], v[172:175], v[188:191], v[116:119]
	v_mfma_f32_16x16x32_bf16 v[112:115], v[180:183], v[188:191], v[112:115]
	v_mfma_f32_16x16x32_bf16 v[100:103], v[172:175], v[196:199], v[100:103]
	v_mfma_f32_16x16x32_bf16 v[96:99], v[180:183], v[196:199], v[96:99]
	v_mfma_f32_16x16x32_bf16 v[84:87], v[172:175], v[204:207], v[84:87]
	v_mfma_f32_16x16x32_bf16 v[80:83], v[180:183], v[204:207], v[80:83]
	v_mfma_f32_16x16x32_bf16 v[76:79], v[172:175], v[212:215], v[76:79]
	v_mfma_f32_16x16x32_bf16 v[72:75], v[180:183], v[212:215], v[72:75]
	s_setprio 0
	s_barrier
	s_add_u32 s20, s18, 0x8000
	s_addc_u32 s21, s19, 0
	s_add_i32 s68, s68, s24
	s_mov_b32 m0, s68
	ds_read_b128 v[184:187], v150 offset:49152
	ds_read_b128 v[188:191], v150 offset:50176
	ds_read_b128 v[192:195], v150 offset:51200
	ds_read_b128 v[196:199], v150 offset:52224
	ds_read_b128 v[200:203], v150 offset:53248
	ds_read_b128 v[204:207], v150 offset:54272
	ds_read_b128 v[208:211], v150 offset:55296
	ds_read_b128 v[212:215], v150 offset:56320
	global_load_lds_dwordx4 v138, s[20:21]
	s_add_i32 m0, s68, 0x2000
	s_add_u32 s18, s18, 0xc000
	s_addc_u32 s19, s19, 0
	global_load_lds_dwordx4 v142, s[20:21]
	s_add_i32 s20, s69, s24
	s_mov_b32 m0, s20
	s_nop 0
	global_load_lds_dwordx4 v138, s[18:19]
	s_add_i32 m0, s20, 0x2000
	s_nop 0
	global_load_lds_dwordx4 v142, s[18:19]
	s_mov_b32 m0, s35
	s_nop 0
	global_load_lds_dwordx4 v136, s[16:17]
	s_mov_b32 m0, s70
	s_nop 0
	global_load_lds_dwordx4 v140, s[16:17]
	s_waitcnt vmcnt(8)
	s_waitcnt lgkmcnt(0)
	s_barrier
	s_setprio 1
	s_waitcnt lgkmcnt(0)
	v_mfma_f32_16x16x32_bf16 v[68:71], v[152:155], v[184:187], v[68:71]
	v_mfma_f32_16x16x32_bf16 v[64:67], v[160:163], v[184:187], v[64:67]
	v_mfma_f32_16x16x32_bf16 v[60:63], v[152:155], v[192:195], v[60:63]
	v_mfma_f32_16x16x32_bf16 v[56:59], v[160:163], v[192:195], v[56:59]
	v_mfma_f32_16x16x32_bf16 v[44:47], v[152:155], v[200:203], v[44:47]
	v_mfma_f32_16x16x32_bf16 v[40:43], v[160:163], v[200:203], v[40:43]
	v_mfma_f32_16x16x32_bf16 v[24:27], v[152:155], v[208:211], v[24:27]
	v_mfma_f32_16x16x32_bf16 v[20:23], v[160:163], v[208:211], v[20:23]
	v_mfma_f32_16x16x32_bf16 v[68:71], v[156:159], v[188:191], v[68:71]
	v_mfma_f32_16x16x32_bf16 v[64:67], v[164:167], v[188:191], v[64:67]
	v_mfma_f32_16x16x32_bf16 v[60:63], v[156:159], v[196:199], v[60:63]
	v_mfma_f32_16x16x32_bf16 v[56:59], v[164:167], v[196:199], v[56:59]
	v_mfma_f32_16x16x32_bf16 v[44:47], v[156:159], v[204:207], v[44:47]
	v_mfma_f32_16x16x32_bf16 v[40:43], v[164:167], v[204:207], v[40:43]
	v_mfma_f32_16x16x32_bf16 v[24:27], v[156:159], v[212:215], v[24:27]
	v_mfma_f32_16x16x32_bf16 v[20:23], v[164:167], v[212:215], v[20:23]
	s_setprio 0
	s_setprio 1
	v_mfma_f32_16x16x32_bf16 v[52:55], v[168:171], v[184:187], v[52:55]
	v_mfma_f32_16x16x32_bf16 v[48:51], v[176:179], v[184:187], v[48:51]
	v_mfma_f32_16x16x32_bf16 v[32:35], v[168:171], v[192:195], v[32:35]
	v_mfma_f32_16x16x32_bf16 v[28:31], v[176:179], v[192:195], v[28:31]
	v_mfma_f32_16x16x32_bf16 v[16:19], v[168:171], v[200:203], v[16:19]
	v_mfma_f32_16x16x32_bf16 v[12:15], v[176:179], v[200:203], v[12:15]
	v_mfma_f32_16x16x32_bf16 v[8:11], v[168:171], v[208:211], v[8:11]
	v_mfma_f32_16x16x32_bf16 v[4:7], v[176:179], v[208:211], v[4:7]
	v_mfma_f32_16x16x32_bf16 v[52:55], v[172:175], v[188:191], v[52:55]
	v_mfma_f32_16x16x32_bf16 v[48:51], v[180:183], v[188:191], v[48:51]
	v_mfma_f32_16x16x32_bf16 v[32:35], v[172:175], v[196:199], v[32:35]
	v_mfma_f32_16x16x32_bf16 v[28:31], v[180:183], v[196:199], v[28:31]
	v_mfma_f32_16x16x32_bf16 v[16:19], v[172:175], v[204:207], v[16:19]
	v_mfma_f32_16x16x32_bf16 v[12:15], v[180:183], v[204:207], v[12:15]
	v_mfma_f32_16x16x32_bf16 v[8:11], v[172:175], v[212:215], v[8:11]
	v_mfma_f32_16x16x32_bf16 v[4:7], v[180:183], v[212:215], v[4:7]
	s_setprio 0
	s_barrier
	s_add_i32 s13, s13, 2
	s_add_u32 s10, s10, 0x10000
	s_addc_u32 s11, s11, 0
	s_add_u32 vcc_lo, vcc_lo, 0x10000
	s_addc_u32 vcc_hi, vcc_hi, 0
	s_cmpk_gt_u32 s13, 0x55
	s_cbranch_scc0 .LBB0_439
	s_and_b64 vcc, exec, s[6:7]
	s_cbranch_vccz .LBB0_442
	s_barrier

; #define PG8_STAGE(bufoff, gbase, voff) do { _Pragma("unroll") for (int _i = 0; _i < 2; ++_i) \
;         __builtin_amdgcn_global_load_lds((const unsigned*)((const char*)(gbase) + (voff)[_i]), (PG8_LAS unsigned*)(lds + (bufoff) + ldsw + _i * 8192), 16, 0, 0); } while (0)
; #define PG8_LDA(dst, b, h) do { _Pragma("unroll") for (int m = 0; m < 4; ++m) _Pragma("unroll") for (int k = 0; k < 2; ++k) dst[m][k] = *(const PG8_LAS bf16x8*)(lds + PG8_SA(b, h) + aoff + m * 2048 + k * 1024); } while (0)
; #define PG8_LDB(dst, b, h) do { _Pragma("unroll") for (int n = 0; n < 2; ++n) _Pragma("unroll") for (int k = 0; k < 2; ++k) dst[n][k] = *(const PG8_LAS bf16x8*)(lds + PG8_SB(b, h) + boff + n * 2048 + k * 1024); } while (0)
; #define PG8_MMA(ai, bj, At, Bt) do { __builtin_amdgcn_s_setprio(1); _Pragma("unroll") for (int m = 0; m < 4; ++m) _Pragma("unroll") for (int n = 0; n < 2; ++n) _Pragma("unroll") for (int k = 0; k < 2; ++k) \
;         acc[ai][bj][m][n] = __builtin_amdgcn_mfma_f32_16x16x32_bf16(Bt[n][k], At[m][k], acc[ai][bj][m][n], 0, 0, 0); __builtin_amdgcn_s_setprio(0); } while (0)
; #define PG8_WAIT_V(n) asm volatile("s_waitcnt vmcnt(" #n ")" ::: "memory")
; template <class Epi, class Sched, bool ALIGN_EPI = false, bool SP2 = false, bool ABLK = false, bool BBLK = false>
; __device__ __forceinline__ void gemm_phase(PG8_LAS unsigned char* lds, const Gemm g, const Sched& S, const Epi& E) {
;     ...
;         for (int t = 0; t < nt; t += 2) {
;             const bool last = (t == nt - 2);
;             const char* a1 = cA + (size_t)(t + 1) * kstepA;
;             const char* a2 = last ? nA : cA + (size_t)(t + 2) * kstepA; const char* b2 = last ? nB : cB + (size_t)(t + 2) * kstepB;
;             const char* a3 = a2 + kstepA; const char* b3 = b2 + kstepB;
;             if (last && has_next) S.a_ready(nxt);
;             if constexpr (SP2) {
;             PG8_LDB(B0, 0, 0); PG8_LDB(B1, 0, 1); PG8_SCHED; PG8_LDA(At, 0, 0); PG8_STAGE(PG8_SA(1, 1), a1 + hstepA, voffA);
;             PG8_WAIT_V(8); PG8_WAIT_L(0); PG8_BAR; PG8_MMA(0, 0, At, B0); PG8_MMA(0, 1, At, B1); PG8_BAR; PG8_SCHED;
;             PG8_LDA(At, 0, 1); PG8_STAGE(PG8_SB(0, 0), b2, voffB); PG8_STAGE(PG8_SB(0, 1), b2 + hstepB, voffB); PG8_STAGE(PG8_SA(0, 0), a2, voffA);
;             PG8_WAIT_V(8); PG8_WAIT_L(0); PG8_BAR; PG8_MMA(1, 0, At, B0); PG8_MMA(1, 1, At, B1); PG8_BAR; PG8_SCHED;
.LBB0_916:
	s_add_u32 s22, s20, 0x4000
	s_addc_u32 s23, s21, 0
	s_cmp_eq_u32 s13, 28
	s_cselect_b32 s26, s19, s22
	s_cselect_b32 s27, s1, s23
	s_cselect_b32 s24, s65, s70
	s_cselect_b32 s25, s9, s71
	s_add_u32 s22, s26, 0x8000
	s_addc_u32 s23, s27, 0
	s_add_i32 s68, 0, 0x10000
	v_add_u32_e32 v36, s68, v155
	s_add_i32 s77, 0, 0x14000
	ds_read_b128 v[150:153], v36
	ds_read_b128 v[158:161], v36 offset:1024
	ds_read_b128 v[162:165], v36 offset:2048
	ds_read_b128 v[166:169], v36 offset:3072
	v_add_u32_e32 v36, s77, v155
	ds_read_b128 v[170:173], v36
	ds_read_b128 v[174:177], v36 offset:1024
	ds_read_b128 v[178:181], v36 offset:2048
	ds_read_b128 v[182:185], v36 offset:3072
	s_add_i32 m0, s31, 0xc000
	ds_read_b128 v[186:189], v157
	ds_read_b128 v[190:193], v157 offset:1024
	ds_read_b128 v[194:197], v157 offset:2048
	ds_read_b128 v[198:201], v157 offset:3072
	ds_read_b128 v[202:205], v157 offset:4096
	ds_read_b128 v[206:209], v157 offset:5120
	ds_read_b128 v[210:213], v157 offset:6144
	ds_read_b128 v[214:217], v157 offset:7168
	global_load_lds_dwordx4 v146, s[20:21]
	s_add_i32 m0, s31, 0xe000
	s_nop 0
	global_load_lds_dwordx4 v148, s[20:21]
	s_waitcnt vmcnt(8)
	s_waitcnt lgkmcnt(0)
	s_barrier
	s_setprio 1
	s_waitcnt lgkmcnt(0)
	v_mfma_f32_16x16x32_bf16 v[132:135], v[150:153], v[186:189], v[132:135]
	v_mfma_f32_16x16x32_bf16 v[128:131], v[162:165], v[186:189], v[128:131]
	v_mfma_f32_16x16x32_bf16 v[124:127], v[150:153], v[194:197], v[124:127]
	v_mfma_f32_16x16x32_bf16 v[116:119], v[162:165], v[194:197], v[116:119]
	v_mfma_f32_16x16x32_bf16 v[108:111], v[150:153], v[202:205], v[108:111]
	v_mfma_f32_16x16x32_bf16 v[100:103], v[162:165], v[202:205], v[100:103]
	v_mfma_f32_16x16x32_bf16 v[92:95], v[150:153], v[210:213], v[92:95]
	v_mfma_f32_16x16x32_bf16 v[84:87], v[162:165], v[210:213], v[84:87]
	v_mfma_f32_16x16x32_bf16 v[132:135], v[158:161], v[190:193], v[132:135]
	v_mfma_f32_16x16x32_bf16 v[128:131], v[166:169], v[190:193], v[128:131]
	v_mfma_f32_16x16x32_bf16 v[124:127], v[158:161], v[198:201], v[124:127]
	v_mfma_f32_16x16x32_bf16 v[116:119], v[166:169], v[198:201], v[116:119]
	v_mfma_f32_16x16x32_bf16 v[108:111], v[158:161], v[206:209], v[108:111]
	v_mfma_f32_16x16x32_bf16 v[100:103], v[166:169], v[206:209], v[100:103]
	v_mfma_f32_16x16x32_bf16 v[92:95], v[158:161], v[214:217], v[92:95]
	v_mfma_f32_16x16x32_bf16 v[84:87], v[166:169], v[214:217], v[84:87]
	s_setprio 0
	s_setprio 1
	v_mfma_f32_16x16x32_bf16 v[120:123], v[170:173], v[186:189], v[120:123]
	v_mfma_f32_16x16x32_bf16 v[112:115], v[178:181], v[186:189], v[112:115]
	v_mfma_f32_16x16x32_bf16 v[104:107], v[170:173], v[194:197], v[104:107]
	v_mfma_f32_16x16x32_bf16 v[96:99], v[178:181], v[194:197], v[96:99]
	v_mfma_f32_16x16x32_bf16 v[88:91], v[170:173], v[202:205], v[88:91]
	v_mfma_f32_16x16x32_bf16 v[80:83], v[178:181], v[202:205], v[80:83]
	v_mfma_f32_16x16x32_bf16 v[76:79], v[170:173], v[210:213], v[76:79]
	v_mfma_f32_16x16x32_bf16 v[72:75], v[178:181], v[210:213], v[72:75]
	v_mfma_f32_16x16x32_bf16 v[120:123], v[174:177], v[190:193], v[120:123]
	v_mfma_f32_16x16x32_bf16 v[112:115], v[182:185], v[190:193], v[112:115]
	v_mfma_f32_16x16x32_bf16 v[104:107], v[174:177], v[198:201], v[104:107]
	v_mfma_f32_16x16x32_bf16 v[96:99], v[182:185], v[198:201], v[96:99]
	v_mfma_f32_16x16x32_bf16 v[88:91], v[174:177], v[206:209], v[88:91]
	v_mfma_f32_16x16x32_bf16 v[80:83], v[182:185], v[206:209], v[80:83]
	v_mfma_f32_16x16x32_bf16 v[76:79], v[174:177], v[214:217], v[76:79]
	v_mfma_f32_16x16x32_bf16 v[72:75], v[182:185], v[214:217], v[72:75]
	s_setprio 0
	s_barrier
	s_add_i32 s68, s68, s29
	s_mov_b32 m0, s68
	ds_read_b128 v[186:189], v157 offset:16384
	ds_read_b128 v[190:193], v157 offset:17408
	ds_read_b128 v[194:197], v157 offset:18432
	ds_read_b128 v[198:201], v157 offset:19456
	ds_read_b128 v[202:205], v157 offset:20480
	ds_read_b128 v[206:209], v157 offset:21504
	ds_read_b128 v[210:213], v157 offset:22528
	ds_read_b128 v[214:217], v157 offset:23552
	global_load_lds_dwordx4 v140, s[24:25]
	s_add_i32 m0, s68, 0x2000
	s_add_u32 s68, s24, 0x4000
	s_addc_u32 s69, s25, 0
	s_add_i32 s77, s77, s29
	global_load_lds_dwordx4 v136, s[24:25]
	s_mov_b32 m0, s77
	s_nop 0
	global_load_lds_dwordx4 v140, s[68:69]
	s_add_i32 m0, s77, 0x2000
	s_nop 0
	global_load_lds_dwordx4 v136, s[68:69]
	s_mov_b32 m0, s31
	s_nop 0
	global_load_lds_dwordx4 v142, s[26:27]
	s_mov_b32 m0, s34
	s_nop 0
	global_load_lds_dwordx4 v138, s[26:27]
	s_waitcnt vmcnt(8)
	s_waitcnt lgkmcnt(0)
	s_barrier
	s_setprio 1
	s_waitcnt lgkmcnt(0)
	v_mfma_f32_16x16x32_bf16 v[68:71], v[150:153], v[186:189], v[68:71]
	v_mfma_f32_16x16x32_bf16 v[64:67], v[162:165], v[186:189], v[64:67]
	v_mfma_f32_16x16x32_bf16 v[60:63], v[150:153], v[194:197], v[60:63]
	v_mfma_f32_16x16x32_bf16 v[52:55], v[162:165], v[194:197], v[52:55]
	v_mfma_f32_16x16x32_bf16 v[44:47], v[150:153], v[202:205], v[44:47]
	v_mfma_f32_16x16x32_bf16 v[32:35], v[162:165], v[202:205], v[32:35]
	v_mfma_f32_16x16x32_bf16 v[24:27], v[150:153], v[210:213], v[24:27]
	v_mfma_f32_16x16x32_bf16 v[16:19], v[162:165], v[210:213], v[16:19]
	v_mfma_f32_16x16x32_bf16 v[68:71], v[158:161], v[190:193], v[68:71]
	v_mfma_f32_16x16x32_bf16 v[64:67], v[166:169], v[190:193], v[64:67]
	v_mfma_f32_16x16x32_bf16 v[60:63], v[158:161], v[198:201], v[60:63]
	v_mfma_f32_16x16x32_bf16 v[52:55], v[166:169], v[198:201], v[52:55]
	v_mfma_f32_16x16x32_bf16 v[44:47], v[158:161], v[206:209], v[44:47]
	v_mfma_f32_16x16x32_bf16 v[32:35], v[166:169], v[206:209], v[32:35]
	v_mfma_f32_16x16x32_bf16 v[24:27], v[158:161], v[214:217], v[24:27]
	v_mfma_f32_16x16x32_bf16 v[16:19], v[166:169], v[214:217], v[16:19]
	s_setprio 0
	s_setprio 1
	v_mfma_f32_16x16x32_bf16 v[56:59], v[170:173], v[186:189], v[56:59]
	v_mfma_f32_16x16x32_bf16 v[48:51], v[178:181], v[186:189], v[48:51]
	v_mfma_f32_16x16x32_bf16 v[40:43], v[170:173], v[194:197], v[40:43]
	v_mfma_f32_16x16x32_bf16 v[28:31], v[178:181], v[194:197], v[28:31]
	v_mfma_f32_16x16x32_bf16 v[20:23], v[170:173], v[202:205], v[20:23]
	v_mfma_f32_16x16x32_bf16 v[12:15], v[178:181], v[202:205], v[12:15]
	v_mfma_f32_16x16x32_bf16 v[8:11], v[170:173], v[210:213], v[8:11]
	v_mfma_f32_16x16x32_bf16 v[4:7], v[178:181], v[210:213], v[4:7]
	v_mfma_f32_16x16x32_bf16 v[56:59], v[174:177], v[190:193], v[56:59]
	v_mfma_f32_16x16x32_bf16 v[48:51], v[182:185], v[190:193], v[48:51]
	v_mfma_f32_16x16x32_bf16 v[40:43], v[174:177], v[198:201], v[40:43]
	v_mfma_f32_16x16x32_bf16 v[28:31], v[182:185], v[198:201], v[28:31]
	v_mfma_f32_16x16x32_bf16 v[20:23], v[174:177], v[206:209], v[20:23]
	v_mfma_f32_16x16x32_bf16 v[12:15], v[182:185], v[206:209], v[12:15]
	v_mfma_f32_16x16x32_bf16 v[8:11], v[174:177], v[214:217], v[8:11]
	v_mfma_f32_16x16x32_bf16 v[4:7], v[182:185], v[214:217], v[4:7]
	s_setprio 0
	s_barrier
; #define PG8_STAGE(bufoff, gbase, voff) do { _Pragma("unroll") for (int _i = 0; _i < 2; ++_i) \
;         __builtin_amdgcn_global_load_lds((const unsigned*)((const char*)(gbase) + (voff)[_i]), (PG8_LAS unsigned*)(lds + (bufoff) + ldsw + _i * 8192), 16, 0, 0); } while (0)
; #define PG8_LDA(dst, b, h) do { _Pragma("unroll") for (int m = 0; m < 4; ++m) _Pragma("unroll") for (int k = 0; k < 2; ++k) dst[m][k] = *(const PG8_LAS bf16x8*)(lds + PG8_SA(b, h) + aoff + m * 2048 + k * 1024); } while (0)
; #define PG8_LDB(dst, b, h) do { _Pragma("unroll") for (int n = 0; n < 2; ++n) _Pragma("unroll") for (int k = 0; k < 2; ++k) dst[n][k] = *(const PG8_LAS bf16x8*)(lds + PG8_SB(b, h) + boff + n * 2048 + k * 1024); } while (0)
; #define PG8_MMA(ai, bj, At, Bt) do { __builtin_amdgcn_s_setprio(1); _Pragma("unroll") for (int m = 0; m < 4; ++m) _Pragma("unroll") for (int n = 0; n < 2; ++n) _Pragma("unroll") for (int k = 0; k < 2; ++k) \
;         acc[ai][bj][m][n] = __builtin_amdgcn_mfma_f32_16x16x32_bf16(Bt[n][k], At[m][k], acc[ai][bj][m][n], 0, 0, 0); __builtin_amdgcn_s_setprio(0); } while (0)
; #define PG8_WAIT_V(n) asm volatile("s_waitcnt vmcnt(" #n ")" ::: "memory")
; #define PG8_WAIT_L(n) asm volatile("s_waitcnt lgkmcnt(" #n ")" ::: "memory")
; #define PG8_BAR __builtin_amdgcn_s_barrier()
; #define PG8_SCHED __builtin_amdgcn_sched_barrier(0)
; template <class Epi, class Sched, bool ALIGN_EPI = false, bool SP2 = false, bool ABLK = false, bool BBLK = false>
; __device__ __forceinline__ void gemm_phase(PG8_LAS unsigned char* lds, const Gemm g, const Sched& S, const Epi& E) {
;     ...
;             PG8_LDB(B0, 1, 0); PG8_LDB(B1, 1, 1); PG8_SCHED; PG8_LDA(At, 1, 0); PG8_STAGE(PG8_SA(0, 1), a2 + hstepA, voffA);
;             PG8_WAIT_V(8); PG8_WAIT_L(0); PG8_BAR; PG8_MMA(0, 0, At, B0); PG8_MMA(0, 1, At, B1); PG8_BAR; PG8_SCHED;
;             PG8_LDA(At, 1, 1); PG8_STAGE(PG8_SB(1, 0), b3, voffB); PG8_STAGE(PG8_SB(1, 1), b3 + hstepB, voffB); PG8_STAGE(PG8_SA(1, 0), a3, voffA);
;             PG8_WAIT_V(8); PG8_WAIT_L(0); PG8_BAR; PG8_MMA(1, 0, At, B0); PG8_MMA(1, 1, At, B1); PG8_BAR; PG8_SCHED;
	s_add_i32 s68, 0, 0x18000
	v_add_u32_e32 v36, s68, v155
	s_add_i32 s69, 0, 0x1c000
	ds_read_b128 v[150:153], v36
	ds_read_b128 v[158:161], v36 offset:1024
	ds_read_b128 v[162:165], v36 offset:2048
	ds_read_b128 v[166:169], v36 offset:3072
	v_add_u32_e32 v36, s69, v155
	ds_read_b128 v[170:173], v36
	ds_read_b128 v[174:177], v36 offset:1024
	ds_read_b128 v[178:181], v36 offset:2048
	ds_read_b128 v[182:185], v36 offset:3072
	s_add_u32 s26, s26, 0x4000
	s_addc_u32 s27, s27, 0
	s_mov_b32 m0, s35
	ds_read_b128 v[186:189], v157 offset:32768
	ds_read_b128 v[190:193], v157 offset:33792
	ds_read_b128 v[194:197], v157 offset:34816
	ds_read_b128 v[198:201], v157 offset:35840
	ds_read_b128 v[202:205], v157 offset:36864
	ds_read_b128 v[206:209], v157 offset:37888
	ds_read_b128 v[210:213], v157 offset:38912
	ds_read_b128 v[214:217], v157 offset:39936
	global_load_lds_dwordx4 v142, s[26:27]
	s_mov_b32 m0, s36
	s_nop 0
	global_load_lds_dwordx4 v138, s[26:27]
	s_waitcnt vmcnt(8)
	s_waitcnt lgkmcnt(0)
	s_barrier
	s_setprio 1
	s_waitcnt lgkmcnt(0)
	v_mfma_f32_16x16x32_bf16 v[132:135], v[150:153], v[186:189], v[132:135]
	v_mfma_f32_16x16x32_bf16 v[128:131], v[162:165], v[186:189], v[128:131]
	v_mfma_f32_16x16x32_bf16 v[124:127], v[150:153], v[194:197], v[124:127]
	v_mfma_f32_16x16x32_bf16 v[116:119], v[162:165], v[194:197], v[116:119]
	v_mfma_f32_16x16x32_bf16 v[108:111], v[150:153], v[202:205], v[108:111]
	v_mfma_f32_16x16x32_bf16 v[100:103], v[162:165], v[202:205], v[100:103]
	v_mfma_f32_16x16x32_bf16 v[92:95], v[150:153], v[210:213], v[92:95]
	v_mfma_f32_16x16x32_bf16 v[84:87], v[162:165], v[210:213], v[84:87]
	v_mfma_f32_16x16x32_bf16 v[132:135], v[158:161], v[190:193], v[132:135]
	v_mfma_f32_16x16x32_bf16 v[128:131], v[166:169], v[190:193], v[128:131]
	v_mfma_f32_16x16x32_bf16 v[124:127], v[158:161], v[198:201], v[124:127]
	v_mfma_f32_16x16x32_bf16 v[116:119], v[166:169], v[198:201], v[116:119]
	v_mfma_f32_16x16x32_bf16 v[108:111], v[158:161], v[206:209], v[108:111]
	v_mfma_f32_16x16x32_bf16 v[100:103], v[166:169], v[206:209], v[100:103]
	v_mfma_f32_16x16x32_bf16 v[92:95], v[158:161], v[214:217], v[92:95]
	v_mfma_f32_16x16x32_bf16 v[84:87], v[166:169], v[214:217], v[84:87]
	s_setprio 0
	s_setprio 1
	v_mfma_f32_16x16x32_bf16 v[120:123], v[170:173], v[186:189], v[120:123]
	v_mfma_f32_16x16x32_bf16 v[112:115], v[178:181], v[186:189], v[112:115]
	v_mfma_f32_16x16x32_bf16 v[104:107], v[170:173], v[194:197], v[104:107]
	v_mfma_f32_16x16x32_bf16 v[96:99], v[178:181], v[194:197], v[96:99]
	v_mfma_f32_16x16x32_bf16 v[88:91], v[170:173], v[202:205], v[88:91]
	v_mfma_f32_16x16x32_bf16 v[80:83], v[178:181], v[202:205], v[80:83]
	v_mfma_f32_16x16x32_bf16 v[76:79], v[170:173], v[210:213], v[76:79]
	v_mfma_f32_16x16x32_bf16 v[72:75], v[178:181], v[210:213], v[72:75]
	v_mfma_f32_16x16x32_bf16 v[120:123], v[174:177], v[190:193], v[120:123]
	v_mfma_f32_16x16x32_bf16 v[112:115], v[182:185], v[190:193], v[112:115]
	v_mfma_f32_16x16x32_bf16 v[104:107], v[174:177], v[198:201], v[104:107]
	v_mfma_f32_16x16x32_bf16 v[96:99], v[182:185], v[198:201], v[96:99]
	v_mfma_f32_16x16x32_bf16 v[88:91], v[174:177], v[206:209], v[88:91]
	v_mfma_f32_16x16x32_bf16 v[80:83], v[182:185], v[206:209], v[80:83]
	v_mfma_f32_16x16x32_bf16 v[76:79], v[174:177], v[214:217], v[76:79]
	v_mfma_f32_16x16x32_bf16 v[72:75], v[182:185], v[214:217], v[72:75]
	s_setprio 0
	s_barrier
	s_add_u32 s26, s24, 0x8000
	s_addc_u32 s27, s25, 0
	s_add_i32 s68, s68, s29
	s_mov_b32 m0, s68
	ds_read_b128 v[186:189], v157 offset:49152
	ds_read_b128 v[190:193], v157 offset:50176
	ds_read_b128 v[194:197], v157 offset:51200
	ds_read_b128 v[198:201], v157 offset:52224
	ds_read_b128 v[202:205], v157 offset:53248
	ds_read_b128 v[206:209], v157 offset:54272
	ds_read_b128 v[210:213], v157 offset:55296
	ds_read_b128 v[214:217], v157 offset:56320
	global_load_lds_dwordx4 v140, s[26:27]
	s_add_i32 m0, s68, 0x2000
	s_add_u32 s24, s24, 0xc000
	s_addc_u32 s25, s25, 0
	global_load_lds_dwordx4 v136, s[26:27]
	s_add_i32 s26, s69, s29
	s_mov_b32 m0, s26
	s_nop 0
	global_load_lds_dwordx4 v140, s[24:25]
	s_add_i32 m0, s26, 0x2000
	s_nop 0
	global_load_lds_dwordx4 v136, s[24:25]
	s_mov_b32 m0, s37
	s_nop 0
	global_load_lds_dwordx4 v142, s[22:23]
	s_mov_b32 m0, s62
	s_nop 0
	global_load_lds_dwordx4 v138, s[22:23]
	s_waitcnt vmcnt(8)
	s_waitcnt lgkmcnt(0)
	s_barrier
	s_setprio 1
	s_waitcnt lgkmcnt(0)
	v_mfma_f32_16x16x32_bf16 v[68:71], v[150:153], v[186:189], v[68:71]
	v_mfma_f32_16x16x32_bf16 v[64:67], v[162:165], v[186:189], v[64:67]
	v_mfma_f32_16x16x32_bf16 v[60:63], v[150:153], v[194:197], v[60:63]
	v_mfma_f32_16x16x32_bf16 v[52:55], v[162:165], v[194:197], v[52:55]
	v_mfma_f32_16x16x32_bf16 v[44:47], v[150:153], v[202:205], v[44:47]
	v_mfma_f32_16x16x32_bf16 v[32:35], v[162:165], v[202:205], v[32:35]
	v_mfma_f32_16x16x32_bf16 v[24:27], v[150:153], v[210:213], v[24:27]
	v_mfma_f32_16x16x32_bf16 v[16:19], v[162:165], v[210:213], v[16:19]
	v_mfma_f32_16x16x32_bf16 v[68:71], v[158:161], v[190:193], v[68:71]
	v_mfma_f32_16x16x32_bf16 v[64:67], v[166:169], v[190:193], v[64:67]
	v_mfma_f32_16x16x32_bf16 v[60:63], v[158:161], v[198:201], v[60:63]
	v_mfma_f32_16x16x32_bf16 v[52:55], v[166:169], v[198:201], v[52:55]
	v_mfma_f32_16x16x32_bf16 v[44:47], v[158:161], v[206:209], v[44:47]
	v_mfma_f32_16x16x32_bf16 v[32:35], v[166:169], v[206:209], v[32:35]
	v_mfma_f32_16x16x32_bf16 v[24:27], v[158:161], v[214:217], v[24:27]
	v_mfma_f32_16x16x32_bf16 v[16:19], v[166:169], v[214:217], v[16:19]
	s_setprio 0
	s_setprio 1
	v_mfma_f32_16x16x32_bf16 v[56:59], v[170:173], v[186:189], v[56:59]
	v_mfma_f32_16x16x32_bf16 v[48:51], v[178:181], v[186:189], v[48:51]
	v_mfma_f32_16x16x32_bf16 v[40:43], v[170:173], v[194:197], v[40:43]
	v_mfma_f32_16x16x32_bf16 v[28:31], v[178:181], v[194:197], v[28:31]
	v_mfma_f32_16x16x32_bf16 v[20:23], v[170:173], v[202:205], v[20:23]
	v_mfma_f32_16x16x32_bf16 v[12:15], v[178:181], v[202:205], v[12:15]
	v_mfma_f32_16x16x32_bf16 v[8:11], v[170:173], v[210:213], v[8:11]
	v_mfma_f32_16x16x32_bf16 v[4:7], v[178:181], v[210:213], v[4:7]
	v_mfma_f32_16x16x32_bf16 v[56:59], v[174:177], v[190:193], v[56:59]
	v_mfma_f32_16x16x32_bf16 v[48:51], v[182:185], v[190:193], v[48:51]
	v_mfma_f32_16x16x32_bf16 v[40:43], v[174:177], v[198:201], v[40:43]
	v_mfma_f32_16x16x32_bf16 v[28:31], v[182:185], v[198:201], v[28:31]
	v_mfma_f32_16x16x32_bf16 v[20:23], v[174:177], v[206:209], v[20:23]
	v_mfma_f32_16x16x32_bf16 v[12:15], v[182:185], v[206:209], v[12:15]
	v_mfma_f32_16x16x32_bf16 v[8:11], v[174:177], v[214:217], v[8:11]
	v_mfma_f32_16x16x32_bf16 v[4:7], v[182:185], v[214:217], v[4:7]
	s_setprio 0
	s_barrier
	s_add_i32 s13, s13, 2
	s_add_u32 s20, s20, 0x10000
	s_addc_u32 s21, s21, 0
	s_add_u32 s70, s70, 0x10000
	s_addc_u32 s71, s71, 0
	s_cmp_gt_u32 s13, 29
	s_cbranch_scc0 .LBB0_916
	s_and_b64 vcc, exec, s[6:7]
	s_cbranch_vccz .LBB0_919
	s_barrier

; #define PG8_STAGE(bufoff, gbase, voff) do { _Pragma("unroll") for (int _i = 0; _i < 2; ++_i) \
;         __builtin_amdgcn_global_load_lds((const unsigned*)((const char*)(gbase) + (voff)[_i]), (PG8_LAS unsigned*)(lds + (bufoff) + ldsw + _i * 8192), 16, 0, 0); } while (0)
; #define PG8_LDA(dst, b, h) do { _Pragma("unroll") for (int m = 0; m < 4; ++m) _Pragma("unroll") for (int k = 0; k < 2; ++k) dst[m][k] = *(const PG8_LAS bf16x8*)(lds + PG8_SA(b, h) + aoff + m * 2048 + k * 1024); } while (0)
; #define PG8_LDB(dst, b, h) do { _Pragma("unroll") for (int n = 0; n < 2; ++n) _Pragma("unroll") for (int k = 0; k < 2; ++k) dst[n][k] = *(const PG8_LAS bf16x8*)(lds + PG8_SB(b, h) + boff + n * 2048 + k * 1024); } while (0)
; #define PG8_MMA(ai, bj, At, Bt) do { __builtin_amdgcn_s_setprio(1); _Pragma("unroll") for (int m = 0; m < 4; ++m) _Pragma("unroll") for (int n = 0; n < 2; ++n) _Pragma("unroll") for (int k = 0; k < 2; ++k) \
;         acc[ai][bj][m][n] = __builtin_amdgcn_mfma_f32_16x16x32_bf16(Bt[n][k], At[m][k], acc[ai][bj][m][n], 0, 0, 0); __builtin_amdgcn_s_setprio(0); } while (0)
; #define PG8_WAIT_V(n) asm volatile("s_waitcnt vmcnt(" #n ")" ::: "memory")
; template <class Epi, class Sched, bool ALIGN_EPI = false, bool SP2 = false, bool ABLK = false, bool BBLK = false>
; __device__ __forceinline__ void gemm_phase(PG8_LAS unsigned char* lds, const Gemm g, const Sched& S, const Epi& E) {
;     ...
;         for (int t = 0; t < nt; t += 2) {
;             const bool last = (t == nt - 2);
;             const char* a1 = cA + (size_t)(t + 1) * kstepA;
;             const char* a2 = last ? nA : cA + (size_t)(t + 2) * kstepA; const char* b2 = last ? nB : cB + (size_t)(t + 2) * kstepB;
;             const char* a3 = a2 + kstepA; const char* b3 = b2 + kstepB;
;             if (last && has_next) S.a_ready(nxt);
;             if constexpr (SP2) {
;             PG8_LDB(B0, 0, 0); PG8_LDB(B1, 0, 1); PG8_SCHED; PG8_LDA(At, 0, 0); PG8_STAGE(PG8_SA(1, 1), a1 + hstepA, voffA);
;             PG8_WAIT_V(8); PG8_WAIT_L(0); PG8_BAR; PG8_MMA(0, 0, At, B0); PG8_MMA(0, 1, At, B1); PG8_BAR; PG8_SCHED;
;             PG8_LDA(At, 0, 1); PG8_STAGE(PG8_SB(0, 0), b2, voffB); PG8_STAGE(PG8_SB(0, 1), b2 + hstepB, voffB); PG8_STAGE(PG8_SA(0, 0), a2, voffA);
;             PG8_WAIT_V(8); PG8_WAIT_L(0); PG8_BAR; PG8_MMA(1, 0, At, B0); PG8_MMA(1, 1, At, B1); PG8_BAR; PG8_SCHED;
.LBB0_2111:
	s_add_u32 s24, s22, 0x4000
	s_addc_u32 s25, s23, 0
	s_cmp_eq_u32 s13, 28
	s_cselect_b32 s28, s17, s24
	s_cselect_b32 s29, s12, s25
	s_cselect_b32 s26, s77, s82
	s_cselect_b32 s27, s11, vcc_lo
	s_add_u32 s24, s28, 0x8000
	s_addc_u32 s25, s29, 0
	s_add_i32 s68, 0, 0x10000
	v_add_u32_e32 v151, s68, v148
	s_add_i32 s88, 0, 0x14000
	ds_read_b128 v[36:39], v151
	ds_read_b128 v[152:155], v151 offset:1024
	ds_read_b128 v[156:159], v151 offset:2048
	ds_read_b128 v[160:163], v151 offset:3072
	v_add_u32_e32 v151, s88, v148
	ds_read_b128 v[164:167], v151
	ds_read_b128 v[168:171], v151 offset:1024
	ds_read_b128 v[172:175], v151 offset:2048
	ds_read_b128 v[176:179], v151 offset:3072
	s_add_i32 m0, s9, 0xc000
	ds_read_b128 v[180:183], v150
	ds_read_b128 v[184:187], v150 offset:1024
	ds_read_b128 v[188:191], v150 offset:2048
	ds_read_b128 v[192:195], v150 offset:3072
	ds_read_b128 v[196:199], v150 offset:4096
	ds_read_b128 v[200:203], v150 offset:5120
	ds_read_b128 v[204:207], v150 offset:6144
	ds_read_b128 v[208:211], v150 offset:7168
	global_load_lds_dwordx4 v144, s[22:23]
	s_add_i32 m0, s9, 0xe000
	s_nop 0
	global_load_lds_dwordx4 v146, s[22:23]
	s_waitcnt vmcnt(8)
	s_waitcnt lgkmcnt(0)
	s_barrier
	s_setprio 1
	s_waitcnt lgkmcnt(0)
	v_mfma_f32_16x16x32_bf16 v[132:135], v[36:39], v[180:183], v[132:135]
	v_mfma_f32_16x16x32_bf16 v[128:131], v[156:159], v[180:183], v[128:131]
	v_mfma_f32_16x16x32_bf16 v[124:127], v[36:39], v[188:191], v[124:127]
	v_mfma_f32_16x16x32_bf16 v[120:123], v[156:159], v[188:191], v[120:123]
	v_mfma_f32_16x16x32_bf16 v[108:111], v[36:39], v[196:199], v[108:111]
	v_mfma_f32_16x16x32_bf16 v[104:107], v[156:159], v[196:199], v[104:107]
	v_mfma_f32_16x16x32_bf16 v[92:95], v[36:39], v[204:207], v[92:95]
	v_mfma_f32_16x16x32_bf16 v[88:91], v[156:159], v[204:207], v[88:91]
	v_mfma_f32_16x16x32_bf16 v[132:135], v[152:155], v[184:187], v[132:135]
	v_mfma_f32_16x16x32_bf16 v[128:131], v[160:163], v[184:187], v[128:131]
	v_mfma_f32_16x16x32_bf16 v[124:127], v[152:155], v[192:195], v[124:127]
	v_mfma_f32_16x16x32_bf16 v[120:123], v[160:163], v[192:195], v[120:123]
	v_mfma_f32_16x16x32_bf16 v[108:111], v[152:155], v[200:203], v[108:111]
	v_mfma_f32_16x16x32_bf16 v[104:107], v[160:163], v[200:203], v[104:107]
	v_mfma_f32_16x16x32_bf16 v[92:95], v[152:155], v[208:211], v[92:95]
	v_mfma_f32_16x16x32_bf16 v[88:91], v[160:163], v[208:211], v[88:91]
	s_setprio 0
	s_setprio 1
	v_mfma_f32_16x16x32_bf16 v[116:119], v[164:167], v[180:183], v[116:119]
	v_mfma_f32_16x16x32_bf16 v[112:115], v[172:175], v[180:183], v[112:115]
	v_mfma_f32_16x16x32_bf16 v[100:103], v[164:167], v[188:191], v[100:103]
	v_mfma_f32_16x16x32_bf16 v[96:99], v[172:175], v[188:191], v[96:99]
	v_mfma_f32_16x16x32_bf16 v[84:87], v[164:167], v[196:199], v[84:87]
	v_mfma_f32_16x16x32_bf16 v[80:83], v[172:175], v[196:199], v[80:83]
	v_mfma_f32_16x16x32_bf16 v[76:79], v[164:167], v[204:207], v[76:79]
	v_mfma_f32_16x16x32_bf16 v[72:75], v[172:175], v[204:207], v[72:75]
	v_mfma_f32_16x16x32_bf16 v[116:119], v[168:171], v[184:187], v[116:119]
	v_mfma_f32_16x16x32_bf16 v[112:115], v[176:179], v[184:187], v[112:115]
	v_mfma_f32_16x16x32_bf16 v[100:103], v[168:171], v[192:195], v[100:103]
	v_mfma_f32_16x16x32_bf16 v[96:99], v[176:179], v[192:195], v[96:99]
	v_mfma_f32_16x16x32_bf16 v[84:87], v[168:171], v[200:203], v[84:87]
	v_mfma_f32_16x16x32_bf16 v[80:83], v[176:179], v[200:203], v[80:83]
	v_mfma_f32_16x16x32_bf16 v[76:79], v[168:171], v[208:211], v[76:79]
	v_mfma_f32_16x16x32_bf16 v[72:75], v[176:179], v[208:211], v[72:75]
	s_setprio 0
	s_barrier
	s_add_i32 s68, s68, s34
	s_mov_b32 m0, s68
	ds_read_b128 v[180:183], v150 offset:16384
	ds_read_b128 v[184:187], v150 offset:17408
	ds_read_b128 v[188:191], v150 offset:18432
	ds_read_b128 v[192:195], v150 offset:19456
	ds_read_b128 v[196:199], v150 offset:20480
	ds_read_b128 v[200:203], v150 offset:21504
	ds_read_b128 v[204:207], v150 offset:22528
	ds_read_b128 v[208:211], v150 offset:23552
	global_load_lds_dwordx4 v138, s[26:27]
	s_add_i32 m0, s68, 0x2000
	s_add_u32 s68, s26, 0x4000
	s_addc_u32 s69, s27, 0
	s_add_i32 s88, s88, s34
	global_load_lds_dwordx4 v142, s[26:27]
	s_mov_b32 m0, s88
	s_nop 0
	global_load_lds_dwordx4 v138, s[68:69]
	s_add_i32 m0, s88, 0x2000
	s_nop 0
	global_load_lds_dwordx4 v142, s[68:69]
	s_mov_b32 m0, s9
	s_nop 0
	global_load_lds_dwordx4 v136, s[28:29]
	s_mov_b32 m0, s35
	s_nop 0
	global_load_lds_dwordx4 v140, s[28:29]
	s_waitcnt vmcnt(8)
	s_waitcnt lgkmcnt(0)
	s_barrier
	s_setprio 1
	s_waitcnt lgkmcnt(0)
	v_mfma_f32_16x16x32_bf16 v[68:71], v[36:39], v[180:183], v[68:71]
	v_mfma_f32_16x16x32_bf16 v[64:67], v[156:159], v[180:183], v[64:67]
	v_mfma_f32_16x16x32_bf16 v[60:63], v[36:39], v[188:191], v[60:63]
	v_mfma_f32_16x16x32_bf16 v[56:59], v[156:159], v[188:191], v[56:59]
	v_mfma_f32_16x16x32_bf16 v[44:47], v[36:39], v[196:199], v[44:47]
	v_mfma_f32_16x16x32_bf16 v[40:43], v[156:159], v[196:199], v[40:43]
	v_mfma_f32_16x16x32_bf16 v[24:27], v[36:39], v[204:207], v[24:27]
	v_mfma_f32_16x16x32_bf16 v[20:23], v[156:159], v[204:207], v[20:23]
	v_mfma_f32_16x16x32_bf16 v[68:71], v[152:155], v[184:187], v[68:71]
	v_mfma_f32_16x16x32_bf16 v[64:67], v[160:163], v[184:187], v[64:67]
	v_mfma_f32_16x16x32_bf16 v[60:63], v[152:155], v[192:195], v[60:63]
	v_mfma_f32_16x16x32_bf16 v[56:59], v[160:163], v[192:195], v[56:59]
	v_mfma_f32_16x16x32_bf16 v[44:47], v[152:155], v[200:203], v[44:47]
	v_mfma_f32_16x16x32_bf16 v[40:43], v[160:163], v[200:203], v[40:43]
	v_mfma_f32_16x16x32_bf16 v[24:27], v[152:155], v[208:211], v[24:27]
	v_mfma_f32_16x16x32_bf16 v[20:23], v[160:163], v[208:211], v[20:23]
	s_setprio 0
	s_setprio 1
	v_mfma_f32_16x16x32_bf16 v[48:51], v[172:175], v[180:183], v[48:51]
	v_mfma_f32_16x16x32_bf16 v[32:35], v[164:167], v[188:191], v[32:35]
	v_mfma_f32_16x16x32_bf16 v[28:31], v[172:175], v[188:191], v[28:31]
	v_mfma_f32_16x16x32_bf16 v[16:19], v[164:167], v[196:199], v[16:19]
	v_mfma_f32_16x16x32_bf16 v[12:15], v[172:175], v[196:199], v[12:15]
	v_mfma_f32_16x16x32_bf16 v[8:11], v[164:167], v[204:207], v[8:11]
	v_mfma_f32_16x16x32_bf16 v[4:7], v[172:175], v[204:207], v[4:7]
	v_mfma_f32_16x16x32_bf16 v[36:39], v[164:167], v[180:183], v[52:55]
	v_mfma_f32_16x16x32_bf16 v[48:51], v[176:179], v[184:187], v[48:51]
	v_mfma_f32_16x16x32_bf16 v[32:35], v[168:171], v[192:195], v[32:35]
	v_mfma_f32_16x16x32_bf16 v[28:31], v[176:179], v[192:195], v[28:31]
	v_mfma_f32_16x16x32_bf16 v[16:19], v[168:171], v[200:203], v[16:19]
	v_mfma_f32_16x16x32_bf16 v[12:15], v[176:179], v[200:203], v[12:15]
	v_mfma_f32_16x16x32_bf16 v[8:11], v[168:171], v[208:211], v[8:11]
	v_mfma_f32_16x16x32_bf16 v[4:7], v[176:179], v[208:211], v[4:7]
	v_mfma_f32_16x16x32_bf16 v[36:39], v[168:171], v[184:187], v[36:39]
	s_setprio 0
	s_barrier
; #define PG8_STAGE(bufoff, gbase, voff) do { _Pragma("unroll") for (int _i = 0; _i < 2; ++_i) \
;         __builtin_amdgcn_global_load_lds((const unsigned*)((const char*)(gbase) + (voff)[_i]), (PG8_LAS unsigned*)(lds + (bufoff) + ldsw + _i * 8192), 16, 0, 0); } while (0)
; #define PG8_LDA(dst, b, h) do { _Pragma("unroll") for (int m = 0; m < 4; ++m) _Pragma("unroll") for (int k = 0; k < 2; ++k) dst[m][k] = *(const PG8_LAS bf16x8*)(lds + PG8_SA(b, h) + aoff + m * 2048 + k * 1024); } while (0)
; #define PG8_LDB(dst, b, h) do { _Pragma("unroll") for (int n = 0; n < 2; ++n) _Pragma("unroll") for (int k = 0; k < 2; ++k) dst[n][k] = *(const PG8_LAS bf16x8*)(lds + PG8_SB(b, h) + boff + n * 2048 + k * 1024); } while (0)
; #define PG8_MMA(ai, bj, At, Bt) do { __builtin_amdgcn_s_setprio(1); _Pragma("unroll") for (int m = 0; m < 4; ++m) _Pragma("unroll") for (int n = 0; n < 2; ++n) _Pragma("unroll") for (int k = 0; k < 2; ++k) \
;         acc[ai][bj][m][n] = __builtin_amdgcn_mfma_f32_16x16x32_bf16(Bt[n][k], At[m][k], acc[ai][bj][m][n], 0, 0, 0); __builtin_amdgcn_s_setprio(0); } while (0)
; #define PG8_WAIT_V(n) asm volatile("s_waitcnt vmcnt(" #n ")" ::: "memory")
; #define PG8_WAIT_L(n) asm volatile("s_waitcnt lgkmcnt(" #n ")" ::: "memory")
; #define PG8_BAR __builtin_amdgcn_s_barrier()
; #define PG8_SCHED __builtin_amdgcn_sched_barrier(0)
; template <class Epi, class Sched, bool ALIGN_EPI = false, bool SP2 = false, bool ABLK = false, bool BBLK = false>
; __device__ __forceinline__ void gemm_phase(PG8_LAS unsigned char* lds, const Gemm g, const Sched& S, const Epi& E) {
;     ...
;             PG8_LDB(B0, 1, 0); PG8_LDB(B1, 1, 1); PG8_SCHED; PG8_LDA(At, 1, 0); PG8_STAGE(PG8_SA(0, 1), a2 + hstepA, voffA);
;             PG8_WAIT_V(8); PG8_WAIT_L(0); PG8_BAR; PG8_MMA(0, 0, At, B0); PG8_MMA(0, 1, At, B1); PG8_BAR; PG8_SCHED;
;             PG8_LDA(At, 1, 1); PG8_STAGE(PG8_SB(1, 0), b3, voffB); PG8_STAGE(PG8_SB(1, 1), b3 + hstepB, voffB); PG8_STAGE(PG8_SA(1, 0), a3, voffA);
;             PG8_WAIT_V(8); PG8_WAIT_L(0); PG8_BAR; PG8_MMA(1, 0, At, B0); PG8_MMA(1, 1, At, B1); PG8_BAR; PG8_SCHED;
	s_add_i32 s68, 0, 0x18000
	v_add_u32_e32 v151, s68, v148
	s_add_i32 s69, 0, 0x1c000
	ds_read_b128 v[52:55], v151
	ds_read_b128 v[152:155], v151 offset:1024
	ds_read_b128 v[156:159], v151 offset:2048
	ds_read_b128 v[160:163], v151 offset:3072
	v_add_u32_e32 v151, s69, v148
	ds_read_b128 v[164:167], v151
	ds_read_b128 v[168:171], v151 offset:1024
	ds_read_b128 v[172:175], v151 offset:2048
	ds_read_b128 v[176:179], v151 offset:3072
	s_add_u32 s28, s28, 0x4000
	s_addc_u32 s29, s29, 0
	s_mov_b32 m0, s36
	ds_read_b128 v[180:183], v150 offset:32768
	ds_read_b128 v[184:187], v150 offset:33792
	ds_read_b128 v[188:191], v150 offset:34816
	ds_read_b128 v[192:195], v150 offset:35840
	ds_read_b128 v[196:199], v150 offset:36864
	ds_read_b128 v[200:203], v150 offset:37888
	ds_read_b128 v[204:207], v150 offset:38912
	ds_read_b128 v[208:211], v150 offset:39936
	global_load_lds_dwordx4 v136, s[28:29]
	s_mov_b32 m0, s37
	s_nop 0
	global_load_lds_dwordx4 v140, s[28:29]
	s_waitcnt vmcnt(8)
	s_waitcnt lgkmcnt(0)
	s_barrier
	s_setprio 1
	s_waitcnt lgkmcnt(0)
	v_mfma_f32_16x16x32_bf16 v[132:135], v[52:55], v[180:183], v[132:135]
	v_mfma_f32_16x16x32_bf16 v[128:131], v[156:159], v[180:183], v[128:131]
	v_mfma_f32_16x16x32_bf16 v[124:127], v[52:55], v[188:191], v[124:127]
	v_mfma_f32_16x16x32_bf16 v[120:123], v[156:159], v[188:191], v[120:123]
	v_mfma_f32_16x16x32_bf16 v[108:111], v[52:55], v[196:199], v[108:111]
	v_mfma_f32_16x16x32_bf16 v[104:107], v[156:159], v[196:199], v[104:107]
	v_mfma_f32_16x16x32_bf16 v[92:95], v[52:55], v[204:207], v[92:95]
	v_mfma_f32_16x16x32_bf16 v[88:91], v[156:159], v[204:207], v[88:91]
	v_mfma_f32_16x16x32_bf16 v[132:135], v[152:155], v[184:187], v[132:135]
	v_mfma_f32_16x16x32_bf16 v[128:131], v[160:163], v[184:187], v[128:131]
	v_mfma_f32_16x16x32_bf16 v[124:127], v[152:155], v[192:195], v[124:127]
	v_mfma_f32_16x16x32_bf16 v[120:123], v[160:163], v[192:195], v[120:123]
	v_mfma_f32_16x16x32_bf16 v[108:111], v[152:155], v[200:203], v[108:111]
	v_mfma_f32_16x16x32_bf16 v[104:107], v[160:163], v[200:203], v[104:107]
	v_mfma_f32_16x16x32_bf16 v[92:95], v[152:155], v[208:211], v[92:95]
	v_mfma_f32_16x16x32_bf16 v[88:91], v[160:163], v[208:211], v[88:91]
	s_setprio 0
	s_setprio 1
	v_mfma_f32_16x16x32_bf16 v[116:119], v[164:167], v[180:183], v[116:119]
	v_mfma_f32_16x16x32_bf16 v[112:115], v[172:175], v[180:183], v[112:115]
	v_mfma_f32_16x16x32_bf16 v[100:103], v[164:167], v[188:191], v[100:103]
	v_mfma_f32_16x16x32_bf16 v[96:99], v[172:175], v[188:191], v[96:99]
	v_mfma_f32_16x16x32_bf16 v[84:87], v[164:167], v[196:199], v[84:87]
	v_mfma_f32_16x16x32_bf16 v[80:83], v[172:175], v[196:199], v[80:83]
	v_mfma_f32_16x16x32_bf16 v[76:79], v[164:167], v[204:207], v[76:79]
	v_mfma_f32_16x16x32_bf16 v[72:75], v[172:175], v[204:207], v[72:75]
	v_mfma_f32_16x16x32_bf16 v[116:119], v[168:171], v[184:187], v[116:119]
	v_mfma_f32_16x16x32_bf16 v[112:115], v[176:179], v[184:187], v[112:115]
	v_mfma_f32_16x16x32_bf16 v[100:103], v[168:171], v[192:195], v[100:103]
	v_mfma_f32_16x16x32_bf16 v[96:99], v[176:179], v[192:195], v[96:99]
	v_mfma_f32_16x16x32_bf16 v[84:87], v[168:171], v[200:203], v[84:87]
	v_mfma_f32_16x16x32_bf16 v[80:83], v[176:179], v[200:203], v[80:83]
	v_mfma_f32_16x16x32_bf16 v[76:79], v[168:171], v[208:211], v[76:79]
	v_mfma_f32_16x16x32_bf16 v[72:75], v[176:179], v[208:211], v[72:75]
	s_setprio 0
	s_barrier
	s_add_u32 s28, s26, 0x8000
	s_addc_u32 s29, s27, 0
	s_add_i32 s68, s68, s34
	s_mov_b32 m0, s68
	ds_read_b128 v[180:183], v150 offset:49152
	ds_read_b128 v[184:187], v150 offset:50176
	ds_read_b128 v[188:191], v150 offset:51200
	ds_read_b128 v[192:195], v150 offset:52224
	ds_read_b128 v[196:199], v150 offset:53248
	ds_read_b128 v[200:203], v150 offset:54272
	ds_read_b128 v[204:207], v150 offset:55296
	ds_read_b128 v[208:211], v150 offset:56320
	global_load_lds_dwordx4 v138, s[28:29]
	s_add_i32 m0, s68, 0x2000
	s_add_u32 s26, s26, 0xc000
	s_addc_u32 s27, s27, 0
	global_load_lds_dwordx4 v142, s[28:29]
	s_add_i32 s28, s69, s34
	s_mov_b32 m0, s28
	s_nop 0
	global_load_lds_dwordx4 v138, s[26:27]
	s_add_i32 m0, s28, 0x2000
	s_nop 0
	global_load_lds_dwordx4 v142, s[26:27]
	s_mov_b32 m0, s64
	s_nop 0
	global_load_lds_dwordx4 v136, s[24:25]
	s_mov_b32 m0, s65
	s_nop 0
	global_load_lds_dwordx4 v140, s[24:25]
	s_waitcnt vmcnt(8)
	s_waitcnt lgkmcnt(0)
	s_barrier
	s_setprio 1
	s_waitcnt lgkmcnt(0)
	v_mfma_f32_16x16x32_bf16 v[68:71], v[52:55], v[180:183], v[68:71]
	v_mfma_f32_16x16x32_bf16 v[64:67], v[156:159], v[180:183], v[64:67]
	v_mfma_f32_16x16x32_bf16 v[60:63], v[52:55], v[188:191], v[60:63]
	v_mfma_f32_16x16x32_bf16 v[56:59], v[156:159], v[188:191], v[56:59]
	v_mfma_f32_16x16x32_bf16 v[44:47], v[52:55], v[196:199], v[44:47]
	v_mfma_f32_16x16x32_bf16 v[40:43], v[156:159], v[196:199], v[40:43]
	v_mfma_f32_16x16x32_bf16 v[24:27], v[52:55], v[204:207], v[24:27]
	v_mfma_f32_16x16x32_bf16 v[20:23], v[156:159], v[204:207], v[20:23]
	v_mfma_f32_16x16x32_bf16 v[68:71], v[152:155], v[184:187], v[68:71]
	v_mfma_f32_16x16x32_bf16 v[64:67], v[160:163], v[184:187], v[64:67]
	v_mfma_f32_16x16x32_bf16 v[60:63], v[152:155], v[192:195], v[60:63]
	v_mfma_f32_16x16x32_bf16 v[56:59], v[160:163], v[192:195], v[56:59]
	v_mfma_f32_16x16x32_bf16 v[44:47], v[152:155], v[200:203], v[44:47]
	v_mfma_f32_16x16x32_bf16 v[40:43], v[160:163], v[200:203], v[40:43]
	v_mfma_f32_16x16x32_bf16 v[24:27], v[152:155], v[208:211], v[24:27]
	v_mfma_f32_16x16x32_bf16 v[20:23], v[160:163], v[208:211], v[20:23]
	s_setprio 0
	s_setprio 1
	v_mfma_f32_16x16x32_bf16 v[36:39], v[164:167], v[180:183], v[36:39]
	v_mfma_f32_16x16x32_bf16 v[52:55], v[168:171], v[184:187], v[36:39]
	v_mfma_f32_16x16x32_bf16 v[36:39], v[172:175], v[180:183], v[48:51]
	v_mfma_f32_16x16x32_bf16 v[32:35], v[164:167], v[188:191], v[32:35]
	v_mfma_f32_16x16x32_bf16 v[28:31], v[172:175], v[188:191], v[28:31]
	v_mfma_f32_16x16x32_bf16 v[16:19], v[164:167], v[196:199], v[16:19]
	v_mfma_f32_16x16x32_bf16 v[12:15], v[172:175], v[196:199], v[12:15]
	v_mfma_f32_16x16x32_bf16 v[8:11], v[164:167], v[204:207], v[8:11]
	v_mfma_f32_16x16x32_bf16 v[4:7], v[172:175], v[204:207], v[4:7]
	v_mfma_f32_16x16x32_bf16 v[48:51], v[176:179], v[184:187], v[36:39]
	v_mfma_f32_16x16x32_bf16 v[32:35], v[168:171], v[192:195], v[32:35]
	v_mfma_f32_16x16x32_bf16 v[28:31], v[176:179], v[192:195], v[28:31]
	v_mfma_f32_16x16x32_bf16 v[16:19], v[168:171], v[200:203], v[16:19]
	v_mfma_f32_16x16x32_bf16 v[12:15], v[176:179], v[200:203], v[12:15]
	v_mfma_f32_16x16x32_bf16 v[8:11], v[168:171], v[208:211], v[8:11]
	v_mfma_f32_16x16x32_bf16 v[4:7], v[176:179], v[208:211], v[4:7]
	s_setprio 0
	s_barrier
	s_add_i32 s13, s13, 2
	s_add_u32 s22, s22, 0x10000
	s_addc_u32 s23, s23, 0
	s_add_u32 s82, s82, 0x10000
	s_addc_u32 vcc_lo, vcc_lo, 0
	s_cmp_gt_u32 s13, 29
	s_cbranch_scc0 .LBB0_2111
	s_and_b64 vcc, exec, s[6:7]
	s_movk_i32 s77, 0x1000
	s_cbranch_vccz .LBB0_2114
	s_barrier
